# adds: hand-written GLA-final phase (PD), weight-conversion wave-index reversal for balance, removed redundant start-of-kernel cg grid sync
# speedup vs baseline: 1.0542x; 1.0175x over previous
_Z10fwd_kernel4Args:
	s_load_dwordx2 s[64:65], s[0:1], 0x110
	s_load_dword s74, s[0:1], 0x118
	s_waitcnt lgkmcnt(0)
	v_and_b32_e32 v194, 0x3ff, v0
	v_lshrrev_b32_e32 v0, 9, v194
	v_lshl_add_u32 v1, v194, 2, 0
	v_xor_b32_e32 v0, 7, v0
	v_add_u32_e32 v1, 0x20000, v1
	v_mov_b32_e32 v2, 0
	s_barrier
	ds_write2st64_b32 v1, v2, v2 offset1:8
	ds_write2st64_b32 v1, v2, v2 offset0:16 offset1:24
	v_or_b32_e32 v1, 0x800, v194
	v_cmp_lt_u32_e32 vcc, 4, v0
	v_cmp_lt_u32_e64 s[4:5], 3, v0
	s_and_saveexec_b64 s[6:7], s[4:5]
	v_lshl_add_u32 v3, v1, 2, 0
	v_add_u32_e32 v3, 0x20000, v3
	ds_write_b32 v3, v2
	s_or_b64 exec, exec, s[6:7]
	s_and_saveexec_b64 s[4:5], vcc
	s_add_i32 s3, 0, 0x20000
	v_lshl_add_u32 v1, v1, 2, s3
	v_mov_b32_e32 v2, 0
	ds_write_b32 v1, v2 offset:2048
	s_or_b64 exec, exec, s[4:5]
	v_or_b32_e32 v1, 0xc00, v194
	v_cmp_lt_u32_e32 vcc, 6, v0
	v_cmp_lt_u32_e64 s[4:5], 5, v0
	s_and_saveexec_b64 s[6:7], s[4:5]
	v_lshl_add_u32 v0, v1, 2, 0
	v_add_u32_e32 v0, 0x20000, v0
	v_mov_b32_e32 v2, 0
	ds_write_b32 v0, v2
	s_or_b64 exec, exec, s[6:7]
	s_and_saveexec_b64 s[4:5], vcc
	s_add_i32 s3, 0, 0x20000
	v_lshl_add_u32 v0, v1, 2, s3
	v_mov_b32_e32 v1, 0
	ds_write_b32 v0, v1 offset:2048
	s_or_b64 exec, exec, s[4:5]
	s_load_dwordx2 s[66:67], s[0:1], 0x108
	s_waitcnt lgkmcnt(0)
	s_barrier
	s_getreg_b32 s3, hwreg(HW_REG_XCC_ID, 0, 4)
	v_cmp_eq_u32_e64 s[46:47], 0, v194
	s_and_saveexec_b64 s[4:5], s[46:47]
	s_cbranch_execz .LBB0_21
	s_mov_b64 s[6:7], exec
	v_mbcnt_lo_u32_b32 v0, s6, 0
	v_mbcnt_hi_u32_b32 v0, s7, v0
	v_cmp_eq_u32_e32 vcc, 0, v0
	s_and_b64 s[8:9], exec, vcc
	s_mov_b64 exec, s[8:9]
	s_cbranch_execz .LBB0_21
	s_lshl_b32 s3, s3, 8
	s_and_b32 s3, s3, 0xf00
	s_add_u32 s8, s66, s3
	s_addc_u32 s9, s67, 0
	s_bcnt1_i32_b64 s3, s[6:7]
	v_mov_b32_e32 v0, 0x1000
	v_mov_b32_e32 v1, s3
	global_atomic_add v0, v1, s[8:9] offset:1024

.LBB0_166:
	s_sub_i32 s10, s11, s10
	s_add_i32 s10, s10, -1
	s_cmpk_gt_i32 s10, 0x6ff
	s_cbranch_scc1 .LBB0_201
	v_mov_b32_e32 v33, 0
	global_load_dwordx2 v[34:35], v33, s[12:13] offset:48
	v_lshlrev_b32_e32 v32, 4, v54
	s_waitcnt vmcnt(2)
	v_lshrrev_b32_e32 v40, 3, v36
	v_lshl_add_u64 v[0:1], s[12:13], 0, v[32:33]
	s_mov_b64 s[0:1], 0x2200000
	v_add_u32_e32 v2, s14, v32
	v_mul_u32_u24_e32 v3, 0x84, v40
	v_mul_u32_u24_e32 v4, 0x420, v54
	v_lshl_add_u64 v[42:43], v[0:1], 0, s[0:1]
	v_lshlrev_b32_e32 v0, 2, v40
	v_lshlrev_b32_e32 v48, 2, v54
	v_add3_u32 v49, s14, v4, v0
	v_mov_b32_e32 v41, v33
	s_lshl_b32 s8, s10, 5
	s_lshl_b32 s9, s11, 5
	s_movk_i32 s15, 0xa00
	s_movk_i32 s16, 0x3480
	v_add_u32_e32 v50, v2, v3
	s_movk_i32 s17, 0x7fff
	s_mov_b32 s18, 0xffff0000
	s_mov_b32 s19, s10
	s_branch .LBB0_169

.LBB0_1240:
	s_or_b64 exec, exec, s[0:1]
	s_mov_b64 s[6:7], s[66:67]
	s_mov_b64 s[0:1], s[68:69]
	s_waitcnt lgkmcnt(0)
	s_barrier
	v_lshrrev_b32_e32 v0, 6, v194
	s_lshl_b32 s19, s64, 3
	v_readfirstlane_b32 s18, v0
	s_lshl_b32 s20, s2, 3
	s_add_i32 s18, s18, s20
	s_cmp_lt_u32 s18, 0x4000
	s_cbranch_scc0 .Lpd_done_L0
	s_add_u32 s0, s66, 0xc800000
	s_addc_u32 s1, s67, 0
	s_add_u32 s14, s66, 0xf800000
	s_addc_u32 s15, s67, 0
	s_add_u32 s16, s66, 0x5800c00
	s_addc_u32 s17, s67, 0
	v_and_b32_e32 v0, 63, v194
	v_mov_b32_e32 v3, 0
	v_lshlrev_b32_e32 v1, 3, v0
	v_mov_b32_e32 v2, 0x358637bd
	global_load_dwordx2 v[12:13], v3, s[66:67] offset:144
	v_and_b32_e32 v8, 31, v0
	v_lshlrev_b32_e32 v8, 4, v8
	v_mov_b32_e32 v9, 0
	s_waitcnt vmcnt(0)
	v_lshl_add_u64 v[12:13], v[12:13], 0, v[8:9]
	global_load_dwordx4 v[4:7], v[12:13], off
.Lpd_loop_L0:
	s_mov_b32 s20, s18
	v_lshl_add_u32 v14, s20, 10, v1
	s_mul_i32 s21, s20, 0x1800
	v_add_u32_e32 v22, s21, v1
	global_load_dwordx2 v[30:31], v14, s[0:1]
	global_load_dwordx2 v[62:63], v14, s[14:15]
	global_load_dwordx2 v[94:95], v22, s[16:17]
	global_load_dwordx2 v[32:33], v14, s[0:1] offset:512
	global_load_dwordx2 v[64:65], v14, s[14:15] offset:512
	global_load_dwordx2 v[96:97], v22, s[16:17] offset:512
	s_mul_i32 s20, s19, 1
	s_add_i32 s20, s20, s18
	s_cmp_lt_u32 s20, 0x4000
	s_cselect_b32 s20, s20, s18
	v_lshl_add_u32 v15, s20, 10, v1
	s_mul_i32 s21, s20, 0x1800
	v_add_u32_e32 v23, s21, v1
	global_load_dwordx2 v[34:35], v15, s[0:1]
	global_load_dwordx2 v[66:67], v15, s[14:15]
	global_load_dwordx2 v[98:99], v23, s[16:17]
	global_load_dwordx2 v[36:37], v15, s[0:1] offset:512
	global_load_dwordx2 v[68:69], v15, s[14:15] offset:512
	global_load_dwordx2 v[100:101], v23, s[16:17] offset:512
	s_mul_i32 s20, s19, 2
	s_add_i32 s20, s20, s18
	s_cmp_lt_u32 s20, 0x4000
	s_cselect_b32 s20, s20, s18
	v_lshl_add_u32 v16, s20, 10, v1
	s_mul_i32 s21, s20, 0x1800
	v_add_u32_e32 v24, s21, v1
	global_load_dwordx2 v[38:39], v16, s[0:1]
	global_load_dwordx2 v[70:71], v16, s[14:15]
	global_load_dwordx2 v[102:103], v24, s[16:17]
	global_load_dwordx2 v[40:41], v16, s[0:1] offset:512
	global_load_dwordx2 v[72:73], v16, s[14:15] offset:512
	global_load_dwordx2 v[104:105], v24, s[16:17] offset:512
	s_mul_i32 s20, s19, 3
	s_add_i32 s20, s20, s18
	s_cmp_lt_u32 s20, 0x4000
	s_cselect_b32 s20, s20, s18
	v_lshl_add_u32 v17, s20, 10, v1
	s_mul_i32 s21, s20, 0x1800
	v_add_u32_e32 v25, s21, v1
	global_load_dwordx2 v[42:43], v17, s[0:1]
	global_load_dwordx2 v[74:75], v17, s[14:15]
	global_load_dwordx2 v[106:107], v25, s[16:17]
	global_load_dwordx2 v[44:45], v17, s[0:1] offset:512
	global_load_dwordx2 v[76:77], v17, s[14:15] offset:512
	global_load_dwordx2 v[108:109], v25, s[16:17] offset:512
	s_mul_i32 s20, s19, 4
	s_add_i32 s20, s20, s18
	s_cmp_lt_u32 s20, 0x4000
	s_cselect_b32 s20, s20, s18
	v_lshl_add_u32 v18, s20, 10, v1
	s_mul_i32 s21, s20, 0x1800
	v_add_u32_e32 v26, s21, v1
	global_load_dwordx2 v[46:47], v18, s[0:1]
	global_load_dwordx2 v[78:79], v18, s[14:15]
	global_load_dwordx2 v[110:111], v26, s[16:17]
	global_load_dwordx2 v[48:49], v18, s[0:1] offset:512
	global_load_dwordx2 v[80:81], v18, s[14:15] offset:512
	global_load_dwordx2 v[112:113], v26, s[16:17] offset:512
	s_mul_i32 s20, s19, 5
	s_add_i32 s20, s20, s18
	s_cmp_lt_u32 s20, 0x4000
	s_cselect_b32 s20, s20, s18
	v_lshl_add_u32 v19, s20, 10, v1
	s_mul_i32 s21, s20, 0x1800
	v_add_u32_e32 v27, s21, v1
	global_load_dwordx2 v[50:51], v19, s[0:1]
	global_load_dwordx2 v[82:83], v19, s[14:15]
	global_load_dwordx2 v[114:115], v27, s[16:17]
	global_load_dwordx2 v[52:53], v19, s[0:1] offset:512
	global_load_dwordx2 v[84:85], v19, s[14:15] offset:512
	global_load_dwordx2 v[116:117], v27, s[16:17] offset:512
	s_mul_i32 s20, s19, 6
	s_add_i32 s20, s20, s18
	s_cmp_lt_u32 s20, 0x4000
	s_cselect_b32 s20, s20, s18
	v_lshl_add_u32 v20, s20, 10, v1
	s_mul_i32 s21, s20, 0x1800
	v_add_u32_e32 v28, s21, v1
	global_load_dwordx2 v[54:55], v20, s[0:1]
	global_load_dwordx2 v[86:87], v20, s[14:15]
	global_load_dwordx2 v[118:119], v28, s[16:17]
	global_load_dwordx2 v[56:57], v20, s[0:1] offset:512
	global_load_dwordx2 v[88:89], v20, s[14:15] offset:512
	global_load_dwordx2 v[120:121], v28, s[16:17] offset:512
	s_mul_i32 s20, s19, 7
	s_add_i32 s20, s20, s18
	s_cmp_lt_u32 s20, 0x4000
	s_cselect_b32 s20, s20, s18
	v_lshl_add_u32 v21, s20, 10, v1
	s_mul_i32 s21, s20, 0x1800
	v_add_u32_e32 v29, s21, v1
	global_load_dwordx2 v[58:59], v21, s[0:1]
	global_load_dwordx2 v[90:91], v21, s[14:15]
	global_load_dwordx2 v[122:123], v29, s[16:17]
	global_load_dwordx2 v[60:61], v21, s[0:1] offset:512
	global_load_dwordx2 v[92:93], v21, s[14:15] offset:512
	global_load_dwordx2 v[124:125], v29, s[16:17] offset:512
	s_waitcnt vmcnt(42)
	v_lshlrev_b32_e32 v128, 16, v30
	v_and_b32_e32 v129, 0xffff0000, v30
	v_lshlrev_b32_e32 v130, 16, v31
	v_and_b32_e32 v131, 0xffff0000, v31
	v_lshlrev_b32_e32 v136, 16, v62
	v_and_b32_e32 v137, 0xffff0000, v62
	v_lshlrev_b32_e32 v138, 16, v63
	v_and_b32_e32 v139, 0xffff0000, v63
	v_lshlrev_b32_e32 v132, 16, v32
	v_and_b32_e32 v133, 0xffff0000, v32
	v_lshlrev_b32_e32 v134, 16, v33
	v_and_b32_e32 v135, 0xffff0000, v33
	v_lshlrev_b32_e32 v140, 16, v64
	v_and_b32_e32 v141, 0xffff0000, v64
	v_lshlrev_b32_e32 v142, 16, v65
	v_and_b32_e32 v143, 0xffff0000, v65
	v_add_f32_e32 v128, v128, v136
	v_add_f32_e32 v129, v129, v137
	v_add_f32_e32 v130, v130, v138
	v_add_f32_e32 v131, v131, v139
	v_add_f32_e32 v132, v132, v140
	v_add_f32_e32 v133, v133, v141
	v_add_f32_e32 v134, v134, v142
	v_add_f32_e32 v135, v135, v143
	v_mul_f32_e32 v160, v128, v128
	v_fmac_f32_e32 v160, v129, v129
	v_fmac_f32_e32 v160, v130, v130
	v_fmac_f32_e32 v160, v131, v131
	v_mul_f32_e32 v161, v132, v132
	v_fmac_f32_e32 v161, v133, v133
	v_fmac_f32_e32 v161, v134, v134
	v_fmac_f32_e32 v161, v135, v135
	v_lshlrev_b32_e32 v144, 16, v94
	v_and_b32_e32 v145, 0xffff0000, v94
	v_lshlrev_b32_e32 v146, 16, v95
	v_and_b32_e32 v147, 0xffff0000, v95
	v_lshlrev_b32_e32 v148, 16, v96
	v_and_b32_e32 v149, 0xffff0000, v96
	v_lshlrev_b32_e32 v150, 16, v97
	v_and_b32_e32 v151, 0xffff0000, v97
	v_add_f32_dpp v160, v160, v160 quad_perm:[1,0,3,2] row_mask:0xf bank_mask:0xf
	v_add_f32_dpp v161, v161, v161 quad_perm:[1,0,3,2] row_mask:0xf bank_mask:0xf
	v_mul_f32_e32 v152, 0xbfb8aa3b, v144
	v_mul_f32_e32 v153, 0xbfb8aa3b, v145
	v_add_f32_dpp v160, v160, v160 quad_perm:[2,3,0,1] row_mask:0xf bank_mask:0xf
	v_add_f32_dpp v161, v161, v161 quad_perm:[2,3,0,1] row_mask:0xf bank_mask:0xf
	v_mul_f32_e32 v154, 0xbfb8aa3b, v146
	v_mul_f32_e32 v155, 0xbfb8aa3b, v147
	v_add_f32_dpp v160, v160, v160 row_half_mirror row_mask:0xf bank_mask:0xf
	v_add_f32_dpp v161, v161, v161 row_half_mirror row_mask:0xf bank_mask:0xf
	v_mul_f32_e32 v156, 0xbfb8aa3b, v148
	v_mul_f32_e32 v157, 0xbfb8aa3b, v149
	v_add_f32_dpp v160, v160, v160 row_mirror row_mask:0xf bank_mask:0xf
	v_add_f32_dpp v161, v161, v161 row_mirror row_mask:0xf bank_mask:0xf
	v_mul_f32_e32 v158, 0xbfb8aa3b, v150
	v_mul_f32_e32 v159, 0xbfb8aa3b, v151
	v_mov_b32_e32 v162, v160
	v_mov_b32_e32 v163, v161
	s_nop 1
	v_permlane16_swap_b32_e32 v160, v162
	v_permlane16_swap_b32_e32 v161, v163
	v_add_f32_e32 v160, v160, v162
	v_add_f32_e32 v161, v161, v163
	v_fmamk_f32 v160, v160, 0x3c000000, v2
	v_fmamk_f32 v161, v161, 0x3c000000, v2
	v_rsq_f32_e32 v160, v160
	v_rsq_f32_e32 v161, v161
	v_exp_f32_e32 v152, v152
	v_exp_f32_e32 v153, v153
	v_exp_f32_e32 v154, v154
	v_exp_f32_e32 v155, v155
	v_exp_f32_e32 v156, v156
	v_exp_f32_e32 v157, v157
	v_exp_f32_e32 v158, v158
	v_exp_f32_e32 v159, v159
	v_add_f32_e32 v152, 1.0, v152
	v_add_f32_e32 v153, 1.0, v153
	v_add_f32_e32 v154, 1.0, v154
	v_add_f32_e32 v155, 1.0, v155
	v_add_f32_e32 v156, 1.0, v156
	v_add_f32_e32 v157, 1.0, v157
	v_add_f32_e32 v158, 1.0, v158
	v_add_f32_e32 v159, 1.0, v159
	v_rcp_f32_e32 v152, v152
	v_rcp_f32_e32 v153, v153
	v_rcp_f32_e32 v154, v154
	v_rcp_f32_e32 v155, v155
	v_rcp_f32_e32 v156, v156
	v_rcp_f32_e32 v157, v157
	v_rcp_f32_e32 v158, v158
	v_rcp_f32_e32 v159, v159
	v_mul_f32_e32 v128, v128, v160
	v_mul_f32_e32 v129, v129, v160
	v_mul_f32_e32 v130, v130, v160
	v_mul_f32_e32 v131, v131, v160
	v_mul_f32_e32 v132, v132, v161
	v_mul_f32_e32 v133, v133, v161
	v_mul_f32_e32 v134, v134, v161
	v_mul_f32_e32 v135, v135, v161
	v_mul_f32_e32 v152, v152, v144
	v_mul_f32_e32 v153, v153, v145
	v_mul_f32_e32 v154, v154, v146
	v_mul_f32_e32 v155, v155, v147
	v_mul_f32_e32 v156, v156, v148
	v_mul_f32_e32 v157, v157, v149
	v_mul_f32_e32 v158, v158, v150
	v_mul_f32_e32 v159, v159, v151
	v_mul_f32_e32 v128, v4, v128
	v_mul_f32_e32 v129, v5, v129
	v_mul_f32_e32 v130, v6, v130
	v_mul_f32_e32 v131, v7, v131
	v_mul_f32_e32 v132, v4, v132
	v_mul_f32_e32 v133, v5, v133
	v_mul_f32_e32 v134, v6, v134
	v_mul_f32_e32 v135, v7, v135
	v_mul_f32_e32 v128, v152, v128
	v_mul_f32_e32 v129, v153, v129
	v_mul_f32_e32 v130, v154, v130
	v_mul_f32_e32 v131, v155, v131
	v_mul_f32_e32 v132, v156, v132
	v_mul_f32_e32 v133, v157, v133
	v_mul_f32_e32 v134, v158, v134
	v_mul_f32_e32 v135, v159, v135
	v_cvt_pk_bf16_f32 v62, v128, v129
	v_cvt_pk_bf16_f32 v63, v130, v131
	v_cvt_pk_bf16_f32 v64, v132, v133
	v_cvt_pk_bf16_f32 v65, v134, v135
	global_store_dwordx2 v14, v[62:63], s[14:15]
	global_store_dwordx2 v14, v[64:65], s[14:15] offset:512
	s_mul_i32 s20, s19, 1
	s_add_i32 s20, s20, s18
	s_cmp_lt_u32 s20, 0x4000
	s_cbranch_scc0 .Lpd_skip_L0_1
	s_waitcnt vmcnt(38)
	v_lshlrev_b32_e32 v128, 16, v34
	v_and_b32_e32 v129, 0xffff0000, v34
	v_lshlrev_b32_e32 v130, 16, v35
	v_and_b32_e32 v131, 0xffff0000, v35
	v_lshlrev_b32_e32 v136, 16, v66
	v_and_b32_e32 v137, 0xffff0000, v66
	v_lshlrev_b32_e32 v138, 16, v67
	v_and_b32_e32 v139, 0xffff0000, v67
	v_lshlrev_b32_e32 v132, 16, v36
	v_and_b32_e32 v133, 0xffff0000, v36
	v_lshlrev_b32_e32 v134, 16, v37
	v_and_b32_e32 v135, 0xffff0000, v37
	v_lshlrev_b32_e32 v140, 16, v68
	v_and_b32_e32 v141, 0xffff0000, v68
	v_lshlrev_b32_e32 v142, 16, v69
	v_and_b32_e32 v143, 0xffff0000, v69
	v_add_f32_e32 v128, v128, v136
	v_add_f32_e32 v129, v129, v137
	v_add_f32_e32 v130, v130, v138
	v_add_f32_e32 v131, v131, v139
	v_add_f32_e32 v132, v132, v140
	v_add_f32_e32 v133, v133, v141
	v_add_f32_e32 v134, v134, v142
	v_add_f32_e32 v135, v135, v143
	v_mul_f32_e32 v160, v128, v128
	v_fmac_f32_e32 v160, v129, v129
	v_fmac_f32_e32 v160, v130, v130
	v_fmac_f32_e32 v160, v131, v131
	v_mul_f32_e32 v161, v132, v132
	v_fmac_f32_e32 v161, v133, v133
	v_fmac_f32_e32 v161, v134, v134
	v_fmac_f32_e32 v161, v135, v135
	v_lshlrev_b32_e32 v144, 16, v98
	v_and_b32_e32 v145, 0xffff0000, v98
	v_lshlrev_b32_e32 v146, 16, v99
	v_and_b32_e32 v147, 0xffff0000, v99
	v_lshlrev_b32_e32 v148, 16, v100
	v_and_b32_e32 v149, 0xffff0000, v100
	v_lshlrev_b32_e32 v150, 16, v101
	v_and_b32_e32 v151, 0xffff0000, v101
	v_add_f32_dpp v160, v160, v160 quad_perm:[1,0,3,2] row_mask:0xf bank_mask:0xf
	v_add_f32_dpp v161, v161, v161 quad_perm:[1,0,3,2] row_mask:0xf bank_mask:0xf
	v_mul_f32_e32 v152, 0xbfb8aa3b, v144
	v_mul_f32_e32 v153, 0xbfb8aa3b, v145
	v_add_f32_dpp v160, v160, v160 quad_perm:[2,3,0,1] row_mask:0xf bank_mask:0xf
	v_add_f32_dpp v161, v161, v161 quad_perm:[2,3,0,1] row_mask:0xf bank_mask:0xf
	v_mul_f32_e32 v154, 0xbfb8aa3b, v146
	v_mul_f32_e32 v155, 0xbfb8aa3b, v147
	v_add_f32_dpp v160, v160, v160 row_half_mirror row_mask:0xf bank_mask:0xf
	v_add_f32_dpp v161, v161, v161 row_half_mirror row_mask:0xf bank_mask:0xf
	v_mul_f32_e32 v156, 0xbfb8aa3b, v148
	v_mul_f32_e32 v157, 0xbfb8aa3b, v149
	v_add_f32_dpp v160, v160, v160 row_mirror row_mask:0xf bank_mask:0xf
	v_add_f32_dpp v161, v161, v161 row_mirror row_mask:0xf bank_mask:0xf
	v_mul_f32_e32 v158, 0xbfb8aa3b, v150
	v_mul_f32_e32 v159, 0xbfb8aa3b, v151
	v_mov_b32_e32 v162, v160
	v_mov_b32_e32 v163, v161
	s_nop 1
	v_permlane16_swap_b32_e32 v160, v162
	v_permlane16_swap_b32_e32 v161, v163
	v_add_f32_e32 v160, v160, v162
	v_add_f32_e32 v161, v161, v163
	v_fmamk_f32 v160, v160, 0x3c000000, v2
	v_fmamk_f32 v161, v161, 0x3c000000, v2
	v_rsq_f32_e32 v160, v160
	v_rsq_f32_e32 v161, v161
	v_exp_f32_e32 v152, v152
	v_exp_f32_e32 v153, v153
	v_exp_f32_e32 v154, v154
	v_exp_f32_e32 v155, v155
	v_exp_f32_e32 v156, v156
	v_exp_f32_e32 v157, v157
	v_exp_f32_e32 v158, v158
	v_exp_f32_e32 v159, v159
	v_add_f32_e32 v152, 1.0, v152
	v_add_f32_e32 v153, 1.0, v153
	v_add_f32_e32 v154, 1.0, v154
	v_add_f32_e32 v155, 1.0, v155
	v_add_f32_e32 v156, 1.0, v156
	v_add_f32_e32 v157, 1.0, v157
	v_add_f32_e32 v158, 1.0, v158
	v_add_f32_e32 v159, 1.0, v159
	v_rcp_f32_e32 v152, v152
	v_rcp_f32_e32 v153, v153
	v_rcp_f32_e32 v154, v154
	v_rcp_f32_e32 v155, v155
	v_rcp_f32_e32 v156, v156
	v_rcp_f32_e32 v157, v157
	v_rcp_f32_e32 v158, v158
	v_rcp_f32_e32 v159, v159
	v_mul_f32_e32 v128, v128, v160
	v_mul_f32_e32 v129, v129, v160
	v_mul_f32_e32 v130, v130, v160
	v_mul_f32_e32 v131, v131, v160
	v_mul_f32_e32 v132, v132, v161
	v_mul_f32_e32 v133, v133, v161
	v_mul_f32_e32 v134, v134, v161
	v_mul_f32_e32 v135, v135, v161
	v_mul_f32_e32 v152, v152, v144
	v_mul_f32_e32 v153, v153, v145
	v_mul_f32_e32 v154, v154, v146
	v_mul_f32_e32 v155, v155, v147
	v_mul_f32_e32 v156, v156, v148
	v_mul_f32_e32 v157, v157, v149
	v_mul_f32_e32 v158, v158, v150
	v_mul_f32_e32 v159, v159, v151
	v_mul_f32_e32 v128, v4, v128
	v_mul_f32_e32 v129, v5, v129
	v_mul_f32_e32 v130, v6, v130
	v_mul_f32_e32 v131, v7, v131
	v_mul_f32_e32 v132, v4, v132
	v_mul_f32_e32 v133, v5, v133
	v_mul_f32_e32 v134, v6, v134
	v_mul_f32_e32 v135, v7, v135
	v_mul_f32_e32 v128, v152, v128
	v_mul_f32_e32 v129, v153, v129
	v_mul_f32_e32 v130, v154, v130
	v_mul_f32_e32 v131, v155, v131
	v_mul_f32_e32 v132, v156, v132
	v_mul_f32_e32 v133, v157, v133
	v_mul_f32_e32 v134, v158, v134
	v_mul_f32_e32 v135, v159, v135
	v_cvt_pk_bf16_f32 v66, v128, v129
	v_cvt_pk_bf16_f32 v67, v130, v131
	v_cvt_pk_bf16_f32 v68, v132, v133
	v_cvt_pk_bf16_f32 v69, v134, v135
	global_store_dwordx2 v15, v[66:67], s[14:15]
	global_store_dwordx2 v15, v[68:69], s[14:15] offset:512
.Lpd_skip_L0_1:
	s_mul_i32 s20, s19, 2
	s_add_i32 s20, s20, s18
	s_cmp_lt_u32 s20, 0x4000
	s_cbranch_scc0 .Lpd_skip_L0_2
	s_waitcnt vmcnt(34)
	v_lshlrev_b32_e32 v128, 16, v38
	v_and_b32_e32 v129, 0xffff0000, v38
	v_lshlrev_b32_e32 v130, 16, v39
	v_and_b32_e32 v131, 0xffff0000, v39
	v_lshlrev_b32_e32 v136, 16, v70
	v_and_b32_e32 v137, 0xffff0000, v70
	v_lshlrev_b32_e32 v138, 16, v71
	v_and_b32_e32 v139, 0xffff0000, v71
	v_lshlrev_b32_e32 v132, 16, v40
	v_and_b32_e32 v133, 0xffff0000, v40
	v_lshlrev_b32_e32 v134, 16, v41
	v_and_b32_e32 v135, 0xffff0000, v41
	v_lshlrev_b32_e32 v140, 16, v72
	v_and_b32_e32 v141, 0xffff0000, v72
	v_lshlrev_b32_e32 v142, 16, v73
	v_and_b32_e32 v143, 0xffff0000, v73
	v_add_f32_e32 v128, v128, v136
	v_add_f32_e32 v129, v129, v137
	v_add_f32_e32 v130, v130, v138
	v_add_f32_e32 v131, v131, v139
	v_add_f32_e32 v132, v132, v140
	v_add_f32_e32 v133, v133, v141
	v_add_f32_e32 v134, v134, v142
	v_add_f32_e32 v135, v135, v143
	v_mul_f32_e32 v160, v128, v128
	v_fmac_f32_e32 v160, v129, v129
	v_fmac_f32_e32 v160, v130, v130
	v_fmac_f32_e32 v160, v131, v131
	v_mul_f32_e32 v161, v132, v132
	v_fmac_f32_e32 v161, v133, v133
	v_fmac_f32_e32 v161, v134, v134
	v_fmac_f32_e32 v161, v135, v135
	v_lshlrev_b32_e32 v144, 16, v102
	v_and_b32_e32 v145, 0xffff0000, v102
	v_lshlrev_b32_e32 v146, 16, v103
	v_and_b32_e32 v147, 0xffff0000, v103
	v_lshlrev_b32_e32 v148, 16, v104
	v_and_b32_e32 v149, 0xffff0000, v104
	v_lshlrev_b32_e32 v150, 16, v105
	v_and_b32_e32 v151, 0xffff0000, v105
	v_add_f32_dpp v160, v160, v160 quad_perm:[1,0,3,2] row_mask:0xf bank_mask:0xf
	v_add_f32_dpp v161, v161, v161 quad_perm:[1,0,3,2] row_mask:0xf bank_mask:0xf
	v_mul_f32_e32 v152, 0xbfb8aa3b, v144
	v_mul_f32_e32 v153, 0xbfb8aa3b, v145
	v_add_f32_dpp v160, v160, v160 quad_perm:[2,3,0,1] row_mask:0xf bank_mask:0xf
	v_add_f32_dpp v161, v161, v161 quad_perm:[2,3,0,1] row_mask:0xf bank_mask:0xf
	v_mul_f32_e32 v154, 0xbfb8aa3b, v146
	v_mul_f32_e32 v155, 0xbfb8aa3b, v147
	v_add_f32_dpp v160, v160, v160 row_half_mirror row_mask:0xf bank_mask:0xf
	v_add_f32_dpp v161, v161, v161 row_half_mirror row_mask:0xf bank_mask:0xf
	v_mul_f32_e32 v156, 0xbfb8aa3b, v148
	v_mul_f32_e32 v157, 0xbfb8aa3b, v149
	v_add_f32_dpp v160, v160, v160 row_mirror row_mask:0xf bank_mask:0xf
	v_add_f32_dpp v161, v161, v161 row_mirror row_mask:0xf bank_mask:0xf
	v_mul_f32_e32 v158, 0xbfb8aa3b, v150
	v_mul_f32_e32 v159, 0xbfb8aa3b, v151
	v_mov_b32_e32 v162, v160
	v_mov_b32_e32 v163, v161
	s_nop 1
	v_permlane16_swap_b32_e32 v160, v162
	v_permlane16_swap_b32_e32 v161, v163
	v_add_f32_e32 v160, v160, v162
	v_add_f32_e32 v161, v161, v163
	v_fmamk_f32 v160, v160, 0x3c000000, v2
	v_fmamk_f32 v161, v161, 0x3c000000, v2
	v_rsq_f32_e32 v160, v160
	v_rsq_f32_e32 v161, v161
	v_exp_f32_e32 v152, v152
	v_exp_f32_e32 v153, v153
	v_exp_f32_e32 v154, v154
	v_exp_f32_e32 v155, v155
	v_exp_f32_e32 v156, v156
	v_exp_f32_e32 v157, v157
	v_exp_f32_e32 v158, v158
	v_exp_f32_e32 v159, v159
	v_add_f32_e32 v152, 1.0, v152
	v_add_f32_e32 v153, 1.0, v153
	v_add_f32_e32 v154, 1.0, v154
	v_add_f32_e32 v155, 1.0, v155
	v_add_f32_e32 v156, 1.0, v156
	v_add_f32_e32 v157, 1.0, v157
	v_add_f32_e32 v158, 1.0, v158
	v_add_f32_e32 v159, 1.0, v159
	v_rcp_f32_e32 v152, v152
	v_rcp_f32_e32 v153, v153
	v_rcp_f32_e32 v154, v154
	v_rcp_f32_e32 v155, v155
	v_rcp_f32_e32 v156, v156
	v_rcp_f32_e32 v157, v157
	v_rcp_f32_e32 v158, v158
	v_rcp_f32_e32 v159, v159
	v_mul_f32_e32 v128, v128, v160
	v_mul_f32_e32 v129, v129, v160
	v_mul_f32_e32 v130, v130, v160
	v_mul_f32_e32 v131, v131, v160
	v_mul_f32_e32 v132, v132, v161
	v_mul_f32_e32 v133, v133, v161
	v_mul_f32_e32 v134, v134, v161
	v_mul_f32_e32 v135, v135, v161
	v_mul_f32_e32 v152, v152, v144
	v_mul_f32_e32 v153, v153, v145
	v_mul_f32_e32 v154, v154, v146
	v_mul_f32_e32 v155, v155, v147
	v_mul_f32_e32 v156, v156, v148
	v_mul_f32_e32 v157, v157, v149
	v_mul_f32_e32 v158, v158, v150
	v_mul_f32_e32 v159, v159, v151
	v_mul_f32_e32 v128, v4, v128
	v_mul_f32_e32 v129, v5, v129
	v_mul_f32_e32 v130, v6, v130
	v_mul_f32_e32 v131, v7, v131
	v_mul_f32_e32 v132, v4, v132
	v_mul_f32_e32 v133, v5, v133
	v_mul_f32_e32 v134, v6, v134
	v_mul_f32_e32 v135, v7, v135
	v_mul_f32_e32 v128, v152, v128
	v_mul_f32_e32 v129, v153, v129
	v_mul_f32_e32 v130, v154, v130
	v_mul_f32_e32 v131, v155, v131
	v_mul_f32_e32 v132, v156, v132
	v_mul_f32_e32 v133, v157, v133
	v_mul_f32_e32 v134, v158, v134
	v_mul_f32_e32 v135, v159, v135
	v_cvt_pk_bf16_f32 v70, v128, v129
	v_cvt_pk_bf16_f32 v71, v130, v131
	v_cvt_pk_bf16_f32 v72, v132, v133
	v_cvt_pk_bf16_f32 v73, v134, v135
	global_store_dwordx2 v16, v[70:71], s[14:15]
	global_store_dwordx2 v16, v[72:73], s[14:15] offset:512
.Lpd_skip_L0_2:
	s_mul_i32 s20, s19, 3
	s_add_i32 s20, s20, s18
	s_cmp_lt_u32 s20, 0x4000
	s_cbranch_scc0 .Lpd_skip_L0_3
	s_waitcnt vmcnt(30)
	v_lshlrev_b32_e32 v128, 16, v42
	v_and_b32_e32 v129, 0xffff0000, v42
	v_lshlrev_b32_e32 v130, 16, v43
	v_and_b32_e32 v131, 0xffff0000, v43
	v_lshlrev_b32_e32 v136, 16, v74
	v_and_b32_e32 v137, 0xffff0000, v74
	v_lshlrev_b32_e32 v138, 16, v75
	v_and_b32_e32 v139, 0xffff0000, v75
	v_lshlrev_b32_e32 v132, 16, v44
	v_and_b32_e32 v133, 0xffff0000, v44
	v_lshlrev_b32_e32 v134, 16, v45
	v_and_b32_e32 v135, 0xffff0000, v45
	v_lshlrev_b32_e32 v140, 16, v76
	v_and_b32_e32 v141, 0xffff0000, v76
	v_lshlrev_b32_e32 v142, 16, v77
	v_and_b32_e32 v143, 0xffff0000, v77
	v_add_f32_e32 v128, v128, v136
	v_add_f32_e32 v129, v129, v137
	v_add_f32_e32 v130, v130, v138
	v_add_f32_e32 v131, v131, v139
	v_add_f32_e32 v132, v132, v140
	v_add_f32_e32 v133, v133, v141
	v_add_f32_e32 v134, v134, v142
	v_add_f32_e32 v135, v135, v143
	v_mul_f32_e32 v160, v128, v128
	v_fmac_f32_e32 v160, v129, v129
	v_fmac_f32_e32 v160, v130, v130
	v_fmac_f32_e32 v160, v131, v131
	v_mul_f32_e32 v161, v132, v132
	v_fmac_f32_e32 v161, v133, v133
	v_fmac_f32_e32 v161, v134, v134
	v_fmac_f32_e32 v161, v135, v135
	v_lshlrev_b32_e32 v144, 16, v106
	v_and_b32_e32 v145, 0xffff0000, v106
	v_lshlrev_b32_e32 v146, 16, v107
	v_and_b32_e32 v147, 0xffff0000, v107
	v_lshlrev_b32_e32 v148, 16, v108
	v_and_b32_e32 v149, 0xffff0000, v108
	v_lshlrev_b32_e32 v150, 16, v109
	v_and_b32_e32 v151, 0xffff0000, v109
	v_add_f32_dpp v160, v160, v160 quad_perm:[1,0,3,2] row_mask:0xf bank_mask:0xf
	v_add_f32_dpp v161, v161, v161 quad_perm:[1,0,3,2] row_mask:0xf bank_mask:0xf
	v_mul_f32_e32 v152, 0xbfb8aa3b, v144
	v_mul_f32_e32 v153, 0xbfb8aa3b, v145
	v_add_f32_dpp v160, v160, v160 quad_perm:[2,3,0,1] row_mask:0xf bank_mask:0xf
	v_add_f32_dpp v161, v161, v161 quad_perm:[2,3,0,1] row_mask:0xf bank_mask:0xf
	v_mul_f32_e32 v154, 0xbfb8aa3b, v146
	v_mul_f32_e32 v155, 0xbfb8aa3b, v147
	v_add_f32_dpp v160, v160, v160 row_half_mirror row_mask:0xf bank_mask:0xf
	v_add_f32_dpp v161, v161, v161 row_half_mirror row_mask:0xf bank_mask:0xf
	v_mul_f32_e32 v156, 0xbfb8aa3b, v148
	v_mul_f32_e32 v157, 0xbfb8aa3b, v149
	v_add_f32_dpp v160, v160, v160 row_mirror row_mask:0xf bank_mask:0xf
	v_add_f32_dpp v161, v161, v161 row_mirror row_mask:0xf bank_mask:0xf
	v_mul_f32_e32 v158, 0xbfb8aa3b, v150
	v_mul_f32_e32 v159, 0xbfb8aa3b, v151
	v_mov_b32_e32 v162, v160
	v_mov_b32_e32 v163, v161
	s_nop 1
	v_permlane16_swap_b32_e32 v160, v162
	v_permlane16_swap_b32_e32 v161, v163
	v_add_f32_e32 v160, v160, v162
	v_add_f32_e32 v161, v161, v163
	v_fmamk_f32 v160, v160, 0x3c000000, v2
	v_fmamk_f32 v161, v161, 0x3c000000, v2
	v_rsq_f32_e32 v160, v160
	v_rsq_f32_e32 v161, v161
	v_exp_f32_e32 v152, v152
	v_exp_f32_e32 v153, v153
	v_exp_f32_e32 v154, v154
	v_exp_f32_e32 v155, v155
	v_exp_f32_e32 v156, v156
	v_exp_f32_e32 v157, v157
	v_exp_f32_e32 v158, v158
	v_exp_f32_e32 v159, v159
	v_add_f32_e32 v152, 1.0, v152
	v_add_f32_e32 v153, 1.0, v153
	v_add_f32_e32 v154, 1.0, v154
	v_add_f32_e32 v155, 1.0, v155
	v_add_f32_e32 v156, 1.0, v156
	v_add_f32_e32 v157, 1.0, v157
	v_add_f32_e32 v158, 1.0, v158
	v_add_f32_e32 v159, 1.0, v159
	v_rcp_f32_e32 v152, v152
	v_rcp_f32_e32 v153, v153
	v_rcp_f32_e32 v154, v154
	v_rcp_f32_e32 v155, v155
	v_rcp_f32_e32 v156, v156
	v_rcp_f32_e32 v157, v157
	v_rcp_f32_e32 v158, v158
	v_rcp_f32_e32 v159, v159
	v_mul_f32_e32 v128, v128, v160
	v_mul_f32_e32 v129, v129, v160
	v_mul_f32_e32 v130, v130, v160
	v_mul_f32_e32 v131, v131, v160
	v_mul_f32_e32 v132, v132, v161
	v_mul_f32_e32 v133, v133, v161
	v_mul_f32_e32 v134, v134, v161
	v_mul_f32_e32 v135, v135, v161
	v_mul_f32_e32 v152, v152, v144
	v_mul_f32_e32 v153, v153, v145
	v_mul_f32_e32 v154, v154, v146
	v_mul_f32_e32 v155, v155, v147
	v_mul_f32_e32 v156, v156, v148
	v_mul_f32_e32 v157, v157, v149
	v_mul_f32_e32 v158, v158, v150
	v_mul_f32_e32 v159, v159, v151
	v_mul_f32_e32 v128, v4, v128
	v_mul_f32_e32 v129, v5, v129
	v_mul_f32_e32 v130, v6, v130
	v_mul_f32_e32 v131, v7, v131
	v_mul_f32_e32 v132, v4, v132
	v_mul_f32_e32 v133, v5, v133
	v_mul_f32_e32 v134, v6, v134
	v_mul_f32_e32 v135, v7, v135
	v_mul_f32_e32 v128, v152, v128
	v_mul_f32_e32 v129, v153, v129
	v_mul_f32_e32 v130, v154, v130
	v_mul_f32_e32 v131, v155, v131
	v_mul_f32_e32 v132, v156, v132
	v_mul_f32_e32 v133, v157, v133
	v_mul_f32_e32 v134, v158, v134
	v_mul_f32_e32 v135, v159, v135
	v_cvt_pk_bf16_f32 v74, v128, v129
	v_cvt_pk_bf16_f32 v75, v130, v131
	v_cvt_pk_bf16_f32 v76, v132, v133
	v_cvt_pk_bf16_f32 v77, v134, v135
	global_store_dwordx2 v17, v[74:75], s[14:15]
	global_store_dwordx2 v17, v[76:77], s[14:15] offset:512
.Lpd_skip_L0_3:
	s_mul_i32 s20, s19, 4
	s_add_i32 s20, s20, s18
	s_cmp_lt_u32 s20, 0x4000
	s_cbranch_scc0 .Lpd_skip_L0_4
	s_waitcnt vmcnt(26)
	v_lshlrev_b32_e32 v128, 16, v46
	v_and_b32_e32 v129, 0xffff0000, v46
	v_lshlrev_b32_e32 v130, 16, v47
	v_and_b32_e32 v131, 0xffff0000, v47
	v_lshlrev_b32_e32 v136, 16, v78
	v_and_b32_e32 v137, 0xffff0000, v78
	v_lshlrev_b32_e32 v138, 16, v79
	v_and_b32_e32 v139, 0xffff0000, v79
	v_lshlrev_b32_e32 v132, 16, v48
	v_and_b32_e32 v133, 0xffff0000, v48
	v_lshlrev_b32_e32 v134, 16, v49
	v_and_b32_e32 v135, 0xffff0000, v49
	v_lshlrev_b32_e32 v140, 16, v80
	v_and_b32_e32 v141, 0xffff0000, v80
	v_lshlrev_b32_e32 v142, 16, v81
	v_and_b32_e32 v143, 0xffff0000, v81
	v_add_f32_e32 v128, v128, v136
	v_add_f32_e32 v129, v129, v137
	v_add_f32_e32 v130, v130, v138
	v_add_f32_e32 v131, v131, v139
	v_add_f32_e32 v132, v132, v140
	v_add_f32_e32 v133, v133, v141
	v_add_f32_e32 v134, v134, v142
	v_add_f32_e32 v135, v135, v143
	v_mul_f32_e32 v160, v128, v128
	v_fmac_f32_e32 v160, v129, v129
	v_fmac_f32_e32 v160, v130, v130
	v_fmac_f32_e32 v160, v131, v131
	v_mul_f32_e32 v161, v132, v132
	v_fmac_f32_e32 v161, v133, v133
	v_fmac_f32_e32 v161, v134, v134
	v_fmac_f32_e32 v161, v135, v135
	v_lshlrev_b32_e32 v144, 16, v110
	v_and_b32_e32 v145, 0xffff0000, v110
	v_lshlrev_b32_e32 v146, 16, v111
	v_and_b32_e32 v147, 0xffff0000, v111
	v_lshlrev_b32_e32 v148, 16, v112
	v_and_b32_e32 v149, 0xffff0000, v112
	v_lshlrev_b32_e32 v150, 16, v113
	v_and_b32_e32 v151, 0xffff0000, v113
	v_add_f32_dpp v160, v160, v160 quad_perm:[1,0,3,2] row_mask:0xf bank_mask:0xf
	v_add_f32_dpp v161, v161, v161 quad_perm:[1,0,3,2] row_mask:0xf bank_mask:0xf
	v_mul_f32_e32 v152, 0xbfb8aa3b, v144
	v_mul_f32_e32 v153, 0xbfb8aa3b, v145
	v_add_f32_dpp v160, v160, v160 quad_perm:[2,3,0,1] row_mask:0xf bank_mask:0xf
	v_add_f32_dpp v161, v161, v161 quad_perm:[2,3,0,1] row_mask:0xf bank_mask:0xf
	v_mul_f32_e32 v154, 0xbfb8aa3b, v146
	v_mul_f32_e32 v155, 0xbfb8aa3b, v147
	v_add_f32_dpp v160, v160, v160 row_half_mirror row_mask:0xf bank_mask:0xf
	v_add_f32_dpp v161, v161, v161 row_half_mirror row_mask:0xf bank_mask:0xf
	v_mul_f32_e32 v156, 0xbfb8aa3b, v148
	v_mul_f32_e32 v157, 0xbfb8aa3b, v149
	v_add_f32_dpp v160, v160, v160 row_mirror row_mask:0xf bank_mask:0xf
	v_add_f32_dpp v161, v161, v161 row_mirror row_mask:0xf bank_mask:0xf
	v_mul_f32_e32 v158, 0xbfb8aa3b, v150
	v_mul_f32_e32 v159, 0xbfb8aa3b, v151
	v_mov_b32_e32 v162, v160
	v_mov_b32_e32 v163, v161
	s_nop 1
	v_permlane16_swap_b32_e32 v160, v162
	v_permlane16_swap_b32_e32 v161, v163
	v_add_f32_e32 v160, v160, v162
	v_add_f32_e32 v161, v161, v163
	v_fmamk_f32 v160, v160, 0x3c000000, v2
	v_fmamk_f32 v161, v161, 0x3c000000, v2
	v_rsq_f32_e32 v160, v160
	v_rsq_f32_e32 v161, v161
	v_exp_f32_e32 v152, v152
	v_exp_f32_e32 v153, v153
	v_exp_f32_e32 v154, v154
	v_exp_f32_e32 v155, v155
	v_exp_f32_e32 v156, v156
	v_exp_f32_e32 v157, v157
	v_exp_f32_e32 v158, v158
	v_exp_f32_e32 v159, v159
	v_add_f32_e32 v152, 1.0, v152
	v_add_f32_e32 v153, 1.0, v153
	v_add_f32_e32 v154, 1.0, v154
	v_add_f32_e32 v155, 1.0, v155
	v_add_f32_e32 v156, 1.0, v156
	v_add_f32_e32 v157, 1.0, v157
	v_add_f32_e32 v158, 1.0, v158
	v_add_f32_e32 v159, 1.0, v159
	v_rcp_f32_e32 v152, v152
	v_rcp_f32_e32 v153, v153
	v_rcp_f32_e32 v154, v154
	v_rcp_f32_e32 v155, v155
	v_rcp_f32_e32 v156, v156
	v_rcp_f32_e32 v157, v157
	v_rcp_f32_e32 v158, v158
	v_rcp_f32_e32 v159, v159
	v_mul_f32_e32 v128, v128, v160
	v_mul_f32_e32 v129, v129, v160
	v_mul_f32_e32 v130, v130, v160
	v_mul_f32_e32 v131, v131, v160
	v_mul_f32_e32 v132, v132, v161
	v_mul_f32_e32 v133, v133, v161
	v_mul_f32_e32 v134, v134, v161
	v_mul_f32_e32 v135, v135, v161
	v_mul_f32_e32 v152, v152, v144
	v_mul_f32_e32 v153, v153, v145
	v_mul_f32_e32 v154, v154, v146
	v_mul_f32_e32 v155, v155, v147
	v_mul_f32_e32 v156, v156, v148
	v_mul_f32_e32 v157, v157, v149
	v_mul_f32_e32 v158, v158, v150
	v_mul_f32_e32 v159, v159, v151
	v_mul_f32_e32 v128, v4, v128
	v_mul_f32_e32 v129, v5, v129
	v_mul_f32_e32 v130, v6, v130
	v_mul_f32_e32 v131, v7, v131
	v_mul_f32_e32 v132, v4, v132
	v_mul_f32_e32 v133, v5, v133
	v_mul_f32_e32 v134, v6, v134
	v_mul_f32_e32 v135, v7, v135
	v_mul_f32_e32 v128, v152, v128
	v_mul_f32_e32 v129, v153, v129
	v_mul_f32_e32 v130, v154, v130
	v_mul_f32_e32 v131, v155, v131
	v_mul_f32_e32 v132, v156, v132
	v_mul_f32_e32 v133, v157, v133
	v_mul_f32_e32 v134, v158, v134
	v_mul_f32_e32 v135, v159, v135
	v_cvt_pk_bf16_f32 v78, v128, v129
	v_cvt_pk_bf16_f32 v79, v130, v131
	v_cvt_pk_bf16_f32 v80, v132, v133
	v_cvt_pk_bf16_f32 v81, v134, v135
	global_store_dwordx2 v18, v[78:79], s[14:15]
	global_store_dwordx2 v18, v[80:81], s[14:15] offset:512
.Lpd_skip_L0_4:
	s_mul_i32 s20, s19, 5
	s_add_i32 s20, s20, s18
	s_cmp_lt_u32 s20, 0x4000
	s_cbranch_scc0 .Lpd_skip_L0_5
	s_waitcnt vmcnt(22)
	v_lshlrev_b32_e32 v128, 16, v50
	v_and_b32_e32 v129, 0xffff0000, v50
	v_lshlrev_b32_e32 v130, 16, v51
	v_and_b32_e32 v131, 0xffff0000, v51
	v_lshlrev_b32_e32 v136, 16, v82
	v_and_b32_e32 v137, 0xffff0000, v82
	v_lshlrev_b32_e32 v138, 16, v83
	v_and_b32_e32 v139, 0xffff0000, v83
	v_lshlrev_b32_e32 v132, 16, v52
	v_and_b32_e32 v133, 0xffff0000, v52
	v_lshlrev_b32_e32 v134, 16, v53
	v_and_b32_e32 v135, 0xffff0000, v53
	v_lshlrev_b32_e32 v140, 16, v84
	v_and_b32_e32 v141, 0xffff0000, v84
	v_lshlrev_b32_e32 v142, 16, v85
	v_and_b32_e32 v143, 0xffff0000, v85
	v_add_f32_e32 v128, v128, v136
	v_add_f32_e32 v129, v129, v137
	v_add_f32_e32 v130, v130, v138
	v_add_f32_e32 v131, v131, v139
	v_add_f32_e32 v132, v132, v140
	v_add_f32_e32 v133, v133, v141
	v_add_f32_e32 v134, v134, v142
	v_add_f32_e32 v135, v135, v143
	v_mul_f32_e32 v160, v128, v128
	v_fmac_f32_e32 v160, v129, v129
	v_fmac_f32_e32 v160, v130, v130
	v_fmac_f32_e32 v160, v131, v131
	v_mul_f32_e32 v161, v132, v132
	v_fmac_f32_e32 v161, v133, v133
	v_fmac_f32_e32 v161, v134, v134
	v_fmac_f32_e32 v161, v135, v135
	v_lshlrev_b32_e32 v144, 16, v114
	v_and_b32_e32 v145, 0xffff0000, v114
	v_lshlrev_b32_e32 v146, 16, v115
	v_and_b32_e32 v147, 0xffff0000, v115
	v_lshlrev_b32_e32 v148, 16, v116
	v_and_b32_e32 v149, 0xffff0000, v116
	v_lshlrev_b32_e32 v150, 16, v117
	v_and_b32_e32 v151, 0xffff0000, v117
	v_add_f32_dpp v160, v160, v160 quad_perm:[1,0,3,2] row_mask:0xf bank_mask:0xf
	v_add_f32_dpp v161, v161, v161 quad_perm:[1,0,3,2] row_mask:0xf bank_mask:0xf
	v_mul_f32_e32 v152, 0xbfb8aa3b, v144
	v_mul_f32_e32 v153, 0xbfb8aa3b, v145
	v_add_f32_dpp v160, v160, v160 quad_perm:[2,3,0,1] row_mask:0xf bank_mask:0xf
	v_add_f32_dpp v161, v161, v161 quad_perm:[2,3,0,1] row_mask:0xf bank_mask:0xf
	v_mul_f32_e32 v154, 0xbfb8aa3b, v146
	v_mul_f32_e32 v155, 0xbfb8aa3b, v147
	v_add_f32_dpp v160, v160, v160 row_half_mirror row_mask:0xf bank_mask:0xf
	v_add_f32_dpp v161, v161, v161 row_half_mirror row_mask:0xf bank_mask:0xf
	v_mul_f32_e32 v156, 0xbfb8aa3b, v148
	v_mul_f32_e32 v157, 0xbfb8aa3b, v149
	v_add_f32_dpp v160, v160, v160 row_mirror row_mask:0xf bank_mask:0xf
	v_add_f32_dpp v161, v161, v161 row_mirror row_mask:0xf bank_mask:0xf
	v_mul_f32_e32 v158, 0xbfb8aa3b, v150
	v_mul_f32_e32 v159, 0xbfb8aa3b, v151
	v_mov_b32_e32 v162, v160
	v_mov_b32_e32 v163, v161
	s_nop 1
	v_permlane16_swap_b32_e32 v160, v162
	v_permlane16_swap_b32_e32 v161, v163
	v_add_f32_e32 v160, v160, v162
	v_add_f32_e32 v161, v161, v163
	v_fmamk_f32 v160, v160, 0x3c000000, v2
	v_fmamk_f32 v161, v161, 0x3c000000, v2
	v_rsq_f32_e32 v160, v160
	v_rsq_f32_e32 v161, v161
	v_exp_f32_e32 v152, v152
	v_exp_f32_e32 v153, v153
	v_exp_f32_e32 v154, v154
	v_exp_f32_e32 v155, v155
	v_exp_f32_e32 v156, v156
	v_exp_f32_e32 v157, v157
	v_exp_f32_e32 v158, v158
	v_exp_f32_e32 v159, v159
	v_add_f32_e32 v152, 1.0, v152
	v_add_f32_e32 v153, 1.0, v153
	v_add_f32_e32 v154, 1.0, v154
	v_add_f32_e32 v155, 1.0, v155
	v_add_f32_e32 v156, 1.0, v156
	v_add_f32_e32 v157, 1.0, v157
	v_add_f32_e32 v158, 1.0, v158
	v_add_f32_e32 v159, 1.0, v159
	v_rcp_f32_e32 v152, v152
	v_rcp_f32_e32 v153, v153
	v_rcp_f32_e32 v154, v154
	v_rcp_f32_e32 v155, v155
	v_rcp_f32_e32 v156, v156
	v_rcp_f32_e32 v157, v157
	v_rcp_f32_e32 v158, v158
	v_rcp_f32_e32 v159, v159
	v_mul_f32_e32 v128, v128, v160
	v_mul_f32_e32 v129, v129, v160
	v_mul_f32_e32 v130, v130, v160
	v_mul_f32_e32 v131, v131, v160
	v_mul_f32_e32 v132, v132, v161
	v_mul_f32_e32 v133, v133, v161
	v_mul_f32_e32 v134, v134, v161
	v_mul_f32_e32 v135, v135, v161
	v_mul_f32_e32 v152, v152, v144
	v_mul_f32_e32 v153, v153, v145
	v_mul_f32_e32 v154, v154, v146
	v_mul_f32_e32 v155, v155, v147
	v_mul_f32_e32 v156, v156, v148
	v_mul_f32_e32 v157, v157, v149
	v_mul_f32_e32 v158, v158, v150
	v_mul_f32_e32 v159, v159, v151
	v_mul_f32_e32 v128, v4, v128
	v_mul_f32_e32 v129, v5, v129
	v_mul_f32_e32 v130, v6, v130
	v_mul_f32_e32 v131, v7, v131
	v_mul_f32_e32 v132, v4, v132
	v_mul_f32_e32 v133, v5, v133
	v_mul_f32_e32 v134, v6, v134
	v_mul_f32_e32 v135, v7, v135
	v_mul_f32_e32 v128, v152, v128
	v_mul_f32_e32 v129, v153, v129
	v_mul_f32_e32 v130, v154, v130
	v_mul_f32_e32 v131, v155, v131
	v_mul_f32_e32 v132, v156, v132
	v_mul_f32_e32 v133, v157, v133
	v_mul_f32_e32 v134, v158, v134
	v_mul_f32_e32 v135, v159, v135
	v_cvt_pk_bf16_f32 v82, v128, v129
	v_cvt_pk_bf16_f32 v83, v130, v131
	v_cvt_pk_bf16_f32 v84, v132, v133
	v_cvt_pk_bf16_f32 v85, v134, v135
	global_store_dwordx2 v19, v[82:83], s[14:15]
	global_store_dwordx2 v19, v[84:85], s[14:15] offset:512
.Lpd_skip_L0_5:
	s_mul_i32 s20, s19, 6
	s_add_i32 s20, s20, s18
	s_cmp_lt_u32 s20, 0x4000
	s_cbranch_scc0 .Lpd_skip_L0_6
	s_waitcnt vmcnt(18)
	v_lshlrev_b32_e32 v128, 16, v54
	v_and_b32_e32 v129, 0xffff0000, v54
	v_lshlrev_b32_e32 v130, 16, v55
	v_and_b32_e32 v131, 0xffff0000, v55
	v_lshlrev_b32_e32 v136, 16, v86
	v_and_b32_e32 v137, 0xffff0000, v86
	v_lshlrev_b32_e32 v138, 16, v87
	v_and_b32_e32 v139, 0xffff0000, v87
	v_lshlrev_b32_e32 v132, 16, v56
	v_and_b32_e32 v133, 0xffff0000, v56
	v_lshlrev_b32_e32 v134, 16, v57
	v_and_b32_e32 v135, 0xffff0000, v57
	v_lshlrev_b32_e32 v140, 16, v88
	v_and_b32_e32 v141, 0xffff0000, v88
	v_lshlrev_b32_e32 v142, 16, v89
	v_and_b32_e32 v143, 0xffff0000, v89
	v_add_f32_e32 v128, v128, v136
	v_add_f32_e32 v129, v129, v137
	v_add_f32_e32 v130, v130, v138
	v_add_f32_e32 v131, v131, v139
	v_add_f32_e32 v132, v132, v140
	v_add_f32_e32 v133, v133, v141
	v_add_f32_e32 v134, v134, v142
	v_add_f32_e32 v135, v135, v143
	v_mul_f32_e32 v160, v128, v128
	v_fmac_f32_e32 v160, v129, v129
	v_fmac_f32_e32 v160, v130, v130
	v_fmac_f32_e32 v160, v131, v131
	v_mul_f32_e32 v161, v132, v132
	v_fmac_f32_e32 v161, v133, v133
	v_fmac_f32_e32 v161, v134, v134
	v_fmac_f32_e32 v161, v135, v135
	v_lshlrev_b32_e32 v144, 16, v118
	v_and_b32_e32 v145, 0xffff0000, v118
	v_lshlrev_b32_e32 v146, 16, v119
	v_and_b32_e32 v147, 0xffff0000, v119
	v_lshlrev_b32_e32 v148, 16, v120
	v_and_b32_e32 v149, 0xffff0000, v120
	v_lshlrev_b32_e32 v150, 16, v121
	v_and_b32_e32 v151, 0xffff0000, v121
	v_add_f32_dpp v160, v160, v160 quad_perm:[1,0,3,2] row_mask:0xf bank_mask:0xf
	v_add_f32_dpp v161, v161, v161 quad_perm:[1,0,3,2] row_mask:0xf bank_mask:0xf
	v_mul_f32_e32 v152, 0xbfb8aa3b, v144
	v_mul_f32_e32 v153, 0xbfb8aa3b, v145
	v_add_f32_dpp v160, v160, v160 quad_perm:[2,3,0,1] row_mask:0xf bank_mask:0xf
	v_add_f32_dpp v161, v161, v161 quad_perm:[2,3,0,1] row_mask:0xf bank_mask:0xf
	v_mul_f32_e32 v154, 0xbfb8aa3b, v146
	v_mul_f32_e32 v155, 0xbfb8aa3b, v147
	v_add_f32_dpp v160, v160, v160 row_half_mirror row_mask:0xf bank_mask:0xf
	v_add_f32_dpp v161, v161, v161 row_half_mirror row_mask:0xf bank_mask:0xf
	v_mul_f32_e32 v156, 0xbfb8aa3b, v148
	v_mul_f32_e32 v157, 0xbfb8aa3b, v149
	v_add_f32_dpp v160, v160, v160 row_mirror row_mask:0xf bank_mask:0xf
	v_add_f32_dpp v161, v161, v161 row_mirror row_mask:0xf bank_mask:0xf
	v_mul_f32_e32 v158, 0xbfb8aa3b, v150
	v_mul_f32_e32 v159, 0xbfb8aa3b, v151
	v_mov_b32_e32 v162, v160
	v_mov_b32_e32 v163, v161
	s_nop 1
	v_permlane16_swap_b32_e32 v160, v162
	v_permlane16_swap_b32_e32 v161, v163
	v_add_f32_e32 v160, v160, v162
	v_add_f32_e32 v161, v161, v163
	v_fmamk_f32 v160, v160, 0x3c000000, v2
	v_fmamk_f32 v161, v161, 0x3c000000, v2
	v_rsq_f32_e32 v160, v160
	v_rsq_f32_e32 v161, v161
	v_exp_f32_e32 v152, v152
	v_exp_f32_e32 v153, v153
	v_exp_f32_e32 v154, v154
	v_exp_f32_e32 v155, v155
	v_exp_f32_e32 v156, v156
	v_exp_f32_e32 v157, v157
	v_exp_f32_e32 v158, v158
	v_exp_f32_e32 v159, v159
	v_add_f32_e32 v152, 1.0, v152
	v_add_f32_e32 v153, 1.0, v153
	v_add_f32_e32 v154, 1.0, v154
	v_add_f32_e32 v155, 1.0, v155
	v_add_f32_e32 v156, 1.0, v156
	v_add_f32_e32 v157, 1.0, v157
	v_add_f32_e32 v158, 1.0, v158
	v_add_f32_e32 v159, 1.0, v159
	v_rcp_f32_e32 v152, v152
	v_rcp_f32_e32 v153, v153
	v_rcp_f32_e32 v154, v154
	v_rcp_f32_e32 v155, v155
	v_rcp_f32_e32 v156, v156
	v_rcp_f32_e32 v157, v157
	v_rcp_f32_e32 v158, v158
	v_rcp_f32_e32 v159, v159
	v_mul_f32_e32 v128, v128, v160
	v_mul_f32_e32 v129, v129, v160
	v_mul_f32_e32 v130, v130, v160
	v_mul_f32_e32 v131, v131, v160
	v_mul_f32_e32 v132, v132, v161
	v_mul_f32_e32 v133, v133, v161
	v_mul_f32_e32 v134, v134, v161
	v_mul_f32_e32 v135, v135, v161
	v_mul_f32_e32 v152, v152, v144
	v_mul_f32_e32 v153, v153, v145
	v_mul_f32_e32 v154, v154, v146
	v_mul_f32_e32 v155, v155, v147
	v_mul_f32_e32 v156, v156, v148
	v_mul_f32_e32 v157, v157, v149
	v_mul_f32_e32 v158, v158, v150
	v_mul_f32_e32 v159, v159, v151
	v_mul_f32_e32 v128, v4, v128
	v_mul_f32_e32 v129, v5, v129
	v_mul_f32_e32 v130, v6, v130
	v_mul_f32_e32 v131, v7, v131
	v_mul_f32_e32 v132, v4, v132
	v_mul_f32_e32 v133, v5, v133
	v_mul_f32_e32 v134, v6, v134
	v_mul_f32_e32 v135, v7, v135
	v_mul_f32_e32 v128, v152, v128
	v_mul_f32_e32 v129, v153, v129
	v_mul_f32_e32 v130, v154, v130
	v_mul_f32_e32 v131, v155, v131
	v_mul_f32_e32 v132, v156, v132
	v_mul_f32_e32 v133, v157, v133
	v_mul_f32_e32 v134, v158, v134
	v_mul_f32_e32 v135, v159, v135
	v_cvt_pk_bf16_f32 v86, v128, v129
	v_cvt_pk_bf16_f32 v87, v130, v131
	v_cvt_pk_bf16_f32 v88, v132, v133
	v_cvt_pk_bf16_f32 v89, v134, v135
	global_store_dwordx2 v20, v[86:87], s[14:15]
	global_store_dwordx2 v20, v[88:89], s[14:15] offset:512
.Lpd_skip_L0_6:
	s_mul_i32 s20, s19, 7
	s_add_i32 s20, s20, s18
	s_cmp_lt_u32 s20, 0x4000
	s_cbranch_scc0 .Lpd_skip_L0_7
	s_waitcnt vmcnt(14)
	v_lshlrev_b32_e32 v128, 16, v58
	v_and_b32_e32 v129, 0xffff0000, v58
	v_lshlrev_b32_e32 v130, 16, v59
	v_and_b32_e32 v131, 0xffff0000, v59
	v_lshlrev_b32_e32 v136, 16, v90
	v_and_b32_e32 v137, 0xffff0000, v90
	v_lshlrev_b32_e32 v138, 16, v91
	v_and_b32_e32 v139, 0xffff0000, v91
	v_lshlrev_b32_e32 v132, 16, v60
	v_and_b32_e32 v133, 0xffff0000, v60
	v_lshlrev_b32_e32 v134, 16, v61
	v_and_b32_e32 v135, 0xffff0000, v61
	v_lshlrev_b32_e32 v140, 16, v92
	v_and_b32_e32 v141, 0xffff0000, v92
	v_lshlrev_b32_e32 v142, 16, v93
	v_and_b32_e32 v143, 0xffff0000, v93
	v_add_f32_e32 v128, v128, v136
	v_add_f32_e32 v129, v129, v137
	v_add_f32_e32 v130, v130, v138
	v_add_f32_e32 v131, v131, v139
	v_add_f32_e32 v132, v132, v140
	v_add_f32_e32 v133, v133, v141
	v_add_f32_e32 v134, v134, v142
	v_add_f32_e32 v135, v135, v143
	v_mul_f32_e32 v160, v128, v128
	v_fmac_f32_e32 v160, v129, v129
	v_fmac_f32_e32 v160, v130, v130
	v_fmac_f32_e32 v160, v131, v131
	v_mul_f32_e32 v161, v132, v132
	v_fmac_f32_e32 v161, v133, v133
	v_fmac_f32_e32 v161, v134, v134
	v_fmac_f32_e32 v161, v135, v135
	v_lshlrev_b32_e32 v144, 16, v122
	v_and_b32_e32 v145, 0xffff0000, v122
	v_lshlrev_b32_e32 v146, 16, v123
	v_and_b32_e32 v147, 0xffff0000, v123
	v_lshlrev_b32_e32 v148, 16, v124
	v_and_b32_e32 v149, 0xffff0000, v124
	v_lshlrev_b32_e32 v150, 16, v125
	v_and_b32_e32 v151, 0xffff0000, v125
	v_add_f32_dpp v160, v160, v160 quad_perm:[1,0,3,2] row_mask:0xf bank_mask:0xf
	v_add_f32_dpp v161, v161, v161 quad_perm:[1,0,3,2] row_mask:0xf bank_mask:0xf
	v_mul_f32_e32 v152, 0xbfb8aa3b, v144
	v_mul_f32_e32 v153, 0xbfb8aa3b, v145
	v_add_f32_dpp v160, v160, v160 quad_perm:[2,3,0,1] row_mask:0xf bank_mask:0xf
	v_add_f32_dpp v161, v161, v161 quad_perm:[2,3,0,1] row_mask:0xf bank_mask:0xf
	v_mul_f32_e32 v154, 0xbfb8aa3b, v146
	v_mul_f32_e32 v155, 0xbfb8aa3b, v147
	v_add_f32_dpp v160, v160, v160 row_half_mirror row_mask:0xf bank_mask:0xf
	v_add_f32_dpp v161, v161, v161 row_half_mirror row_mask:0xf bank_mask:0xf
	v_mul_f32_e32 v156, 0xbfb8aa3b, v148
	v_mul_f32_e32 v157, 0xbfb8aa3b, v149
	v_add_f32_dpp v160, v160, v160 row_mirror row_mask:0xf bank_mask:0xf
	v_add_f32_dpp v161, v161, v161 row_mirror row_mask:0xf bank_mask:0xf
	v_mul_f32_e32 v158, 0xbfb8aa3b, v150
	v_mul_f32_e32 v159, 0xbfb8aa3b, v151
	v_mov_b32_e32 v162, v160
	v_mov_b32_e32 v163, v161
	s_nop 1
	v_permlane16_swap_b32_e32 v160, v162
	v_permlane16_swap_b32_e32 v161, v163
	v_add_f32_e32 v160, v160, v162
	v_add_f32_e32 v161, v161, v163
	v_fmamk_f32 v160, v160, 0x3c000000, v2
	v_fmamk_f32 v161, v161, 0x3c000000, v2
	v_rsq_f32_e32 v160, v160
	v_rsq_f32_e32 v161, v161
	v_exp_f32_e32 v152, v152
	v_exp_f32_e32 v153, v153
	v_exp_f32_e32 v154, v154
	v_exp_f32_e32 v155, v155
	v_exp_f32_e32 v156, v156
	v_exp_f32_e32 v157, v157
	v_exp_f32_e32 v158, v158
	v_exp_f32_e32 v159, v159
	v_add_f32_e32 v152, 1.0, v152
	v_add_f32_e32 v153, 1.0, v153
	v_add_f32_e32 v154, 1.0, v154
	v_add_f32_e32 v155, 1.0, v155
	v_add_f32_e32 v156, 1.0, v156
	v_add_f32_e32 v157, 1.0, v157
	v_add_f32_e32 v158, 1.0, v158
	v_add_f32_e32 v159, 1.0, v159
	v_rcp_f32_e32 v152, v152
	v_rcp_f32_e32 v153, v153
	v_rcp_f32_e32 v154, v154
	v_rcp_f32_e32 v155, v155
	v_rcp_f32_e32 v156, v156
	v_rcp_f32_e32 v157, v157
	v_rcp_f32_e32 v158, v158
	v_rcp_f32_e32 v159, v159
	v_mul_f32_e32 v128, v128, v160
	v_mul_f32_e32 v129, v129, v160
	v_mul_f32_e32 v130, v130, v160
	v_mul_f32_e32 v131, v131, v160
	v_mul_f32_e32 v132, v132, v161
	v_mul_f32_e32 v133, v133, v161
	v_mul_f32_e32 v134, v134, v161
	v_mul_f32_e32 v135, v135, v161
	v_mul_f32_e32 v152, v152, v144
	v_mul_f32_e32 v153, v153, v145
	v_mul_f32_e32 v154, v154, v146
	v_mul_f32_e32 v155, v155, v147
	v_mul_f32_e32 v156, v156, v148
	v_mul_f32_e32 v157, v157, v149
	v_mul_f32_e32 v158, v158, v150
	v_mul_f32_e32 v159, v159, v151
	v_mul_f32_e32 v128, v4, v128
	v_mul_f32_e32 v129, v5, v129
	v_mul_f32_e32 v130, v6, v130
	v_mul_f32_e32 v131, v7, v131
	v_mul_f32_e32 v132, v4, v132
	v_mul_f32_e32 v133, v5, v133
	v_mul_f32_e32 v134, v6, v134
	v_mul_f32_e32 v135, v7, v135
	v_mul_f32_e32 v128, v152, v128
	v_mul_f32_e32 v129, v153, v129
	v_mul_f32_e32 v130, v154, v130
	v_mul_f32_e32 v131, v155, v131
	v_mul_f32_e32 v132, v156, v132
	v_mul_f32_e32 v133, v157, v133
	v_mul_f32_e32 v134, v158, v134
	v_mul_f32_e32 v135, v159, v135
	v_cvt_pk_bf16_f32 v90, v128, v129
	v_cvt_pk_bf16_f32 v91, v130, v131
	v_cvt_pk_bf16_f32 v92, v132, v133
	v_cvt_pk_bf16_f32 v93, v134, v135
	global_store_dwordx2 v21, v[90:91], s[14:15]
	global_store_dwordx2 v21, v[92:93], s[14:15] offset:512
.Lpd_skip_L0_7:
	s_mul_i32 s20, s19, 8
	s_add_i32 s18, s18, s20
	s_cmp_lt_u32 s18, 0x4000
	s_cbranch_scc1 .Lpd_loop_L0

.LBB0_1878:
	s_sub_i32 s18, s19, s18
	s_add_i32 s18, s18, -1
	s_mov_b64 s[0:1], 0x1000
	s_cmpk_gt_i32 s18, 0x6ff
	s_waitcnt vmcnt(0)
	v_lshl_add_u64 v[34:35], v[4:5], 0, s[0:1]
	s_cbranch_scc1 .LBB0_1913
	v_mov_b32_e32 v37, 0
	global_load_dwordx2 v[0:1], v37, s[20:21] offset:48
	v_lshrrev_b32_e32 v49, 3, v32
	v_lshlrev_b32_e32 v36, 4, v48
	s_mov_b64 s[0:1], 0xd20000
	v_mul_u32_u24_e32 v4, 0x420, v48
	s_mov_b64 s[14:15], 0x2200000
	v_add_u32_e32 v5, s22, v36
	v_mul_u32_u24_e32 v6, 0x84, v49
	v_lshl_add_u64 v[2:3], s[20:21], 0, v[36:37]
	v_lshlrev_b32_e32 v7, 2, v49
	v_lshlrev_b32_e32 v50, 2, v48
	s_lshl_b32 s23, s18, 5
	s_lshl_b32 s24, s19, 5
	s_movk_i32 s25, 0xa00
	s_movk_i32 s27, 0x3480
	s_movk_i32 s28, 0x7fff
	s_mov_b32 s29, 0xffff0000
	v_or_b32_e32 v51, 8, v49
	v_or_b32_e32 v52, 16, v49
	v_or_b32_e32 v53, 24, v49
	v_or_b32_e32 v54, 32, v49
	v_or_b32_e32 v55, 40, v49
	v_or_b32_e32 v56, 48, v49
	v_or_b32_e32 v57, 56, v49
	v_lshl_add_u64 v[38:39], v[2:3], 0, s[14:15]
	v_add3_u32 v58, s22, v4, v7
	v_add_u32_e32 v59, v5, v6
	s_mov_b32 s30, s18
	s_waitcnt vmcnt(0)
	v_lshl_add_u64 v[40:41], v[0:1], 0, s[0:1]
	s_branch .LBB0_1881

.LBB0_2850:
	s_or_b64 exec, exec, s[0:1]
	s_mov_b64 s[8:9], s[66:67]
	s_mov_b64 s[0:1], s[68:69]
	s_waitcnt lgkmcnt(0)
	s_barrier
	v_lshrrev_b32_e32 v0, 6, v194
	s_lshl_b32 s15, s64, 3
	v_readfirstlane_b32 s14, v0
	s_lshl_b32 s16, s2, 3
	s_add_i32 s14, s14, s16
	s_cmp_lt_u32 s14, 0x4000
	s_cbranch_scc0 .Lpd_done_L1
	s_add_u32 s0, s66, 0xc800000
	s_addc_u32 s1, s67, 0
	s_add_u32 s10, s66, 0xf800000
	s_addc_u32 s11, s67, 0
	s_add_u32 s12, s66, 0x5800c00
	s_addc_u32 s13, s67, 0
	v_and_b32_e32 v0, 63, v194
	v_mov_b32_e32 v3, 0
	v_lshlrev_b32_e32 v1, 3, v0
	v_mov_b32_e32 v2, 0x358637bd
	global_load_dwordx2 v[12:13], v3, s[66:67] offset:144
	v_and_b32_e32 v8, 31, v0
	v_lshlrev_b32_e32 v8, 4, v8
	v_mov_b32_e32 v9, 0
	s_waitcnt vmcnt(0)
	v_lshl_add_u64 v[12:13], v[12:13], 0, v[8:9]
	global_load_dwordx4 v[4:7], v[12:13], off offset:512
.Lpd_loop_L1:
	s_mov_b32 s16, s14
	v_lshl_add_u32 v14, s16, 10, v1
	s_mul_i32 s17, s16, 0x1800
	v_add_u32_e32 v22, s17, v1
	global_load_dwordx2 v[30:31], v14, s[0:1]
	global_load_dwordx2 v[62:63], v14, s[10:11]
	global_load_dwordx2 v[94:95], v22, s[12:13]
	global_load_dwordx2 v[32:33], v14, s[0:1] offset:512
	global_load_dwordx2 v[64:65], v14, s[10:11] offset:512
	global_load_dwordx2 v[96:97], v22, s[12:13] offset:512
	s_mul_i32 s16, s15, 1
	s_add_i32 s16, s16, s14
	s_cmp_lt_u32 s16, 0x4000
	s_cselect_b32 s16, s16, s14
	v_lshl_add_u32 v15, s16, 10, v1
	s_mul_i32 s17, s16, 0x1800
	v_add_u32_e32 v23, s17, v1
	global_load_dwordx2 v[34:35], v15, s[0:1]
	global_load_dwordx2 v[66:67], v15, s[10:11]
	global_load_dwordx2 v[98:99], v23, s[12:13]
	global_load_dwordx2 v[36:37], v15, s[0:1] offset:512
	global_load_dwordx2 v[68:69], v15, s[10:11] offset:512
	global_load_dwordx2 v[100:101], v23, s[12:13] offset:512
	s_mul_i32 s16, s15, 2
	s_add_i32 s16, s16, s14
	s_cmp_lt_u32 s16, 0x4000
	s_cselect_b32 s16, s16, s14
	v_lshl_add_u32 v16, s16, 10, v1
	s_mul_i32 s17, s16, 0x1800
	v_add_u32_e32 v24, s17, v1
	global_load_dwordx2 v[38:39], v16, s[0:1]
	global_load_dwordx2 v[70:71], v16, s[10:11]
	global_load_dwordx2 v[102:103], v24, s[12:13]
	global_load_dwordx2 v[40:41], v16, s[0:1] offset:512
	global_load_dwordx2 v[72:73], v16, s[10:11] offset:512
	global_load_dwordx2 v[104:105], v24, s[12:13] offset:512
	s_mul_i32 s16, s15, 3
	s_add_i32 s16, s16, s14
	s_cmp_lt_u32 s16, 0x4000
	s_cselect_b32 s16, s16, s14
	v_lshl_add_u32 v17, s16, 10, v1
	s_mul_i32 s17, s16, 0x1800
	v_add_u32_e32 v25, s17, v1
	global_load_dwordx2 v[42:43], v17, s[0:1]
	global_load_dwordx2 v[74:75], v17, s[10:11]
	global_load_dwordx2 v[106:107], v25, s[12:13]
	global_load_dwordx2 v[44:45], v17, s[0:1] offset:512
	global_load_dwordx2 v[76:77], v17, s[10:11] offset:512
	global_load_dwordx2 v[108:109], v25, s[12:13] offset:512
	s_mul_i32 s16, s15, 4
	s_add_i32 s16, s16, s14
	s_cmp_lt_u32 s16, 0x4000
	s_cselect_b32 s16, s16, s14
	v_lshl_add_u32 v18, s16, 10, v1
	s_mul_i32 s17, s16, 0x1800
	v_add_u32_e32 v26, s17, v1
	global_load_dwordx2 v[46:47], v18, s[0:1]
	global_load_dwordx2 v[78:79], v18, s[10:11]
	global_load_dwordx2 v[110:111], v26, s[12:13]
	global_load_dwordx2 v[48:49], v18, s[0:1] offset:512
	global_load_dwordx2 v[80:81], v18, s[10:11] offset:512
	global_load_dwordx2 v[112:113], v26, s[12:13] offset:512
	s_mul_i32 s16, s15, 5
	s_add_i32 s16, s16, s14
	s_cmp_lt_u32 s16, 0x4000
	s_cselect_b32 s16, s16, s14
	v_lshl_add_u32 v19, s16, 10, v1
	s_mul_i32 s17, s16, 0x1800
	v_add_u32_e32 v27, s17, v1
	global_load_dwordx2 v[50:51], v19, s[0:1]
	global_load_dwordx2 v[82:83], v19, s[10:11]
	global_load_dwordx2 v[114:115], v27, s[12:13]
	global_load_dwordx2 v[52:53], v19, s[0:1] offset:512
	global_load_dwordx2 v[84:85], v19, s[10:11] offset:512
	global_load_dwordx2 v[116:117], v27, s[12:13] offset:512
	s_mul_i32 s16, s15, 6
	s_add_i32 s16, s16, s14
	s_cmp_lt_u32 s16, 0x4000
	s_cselect_b32 s16, s16, s14
	v_lshl_add_u32 v20, s16, 10, v1
	s_mul_i32 s17, s16, 0x1800
	v_add_u32_e32 v28, s17, v1
	global_load_dwordx2 v[54:55], v20, s[0:1]
	global_load_dwordx2 v[86:87], v20, s[10:11]
	global_load_dwordx2 v[118:119], v28, s[12:13]
	global_load_dwordx2 v[56:57], v20, s[0:1] offset:512
	global_load_dwordx2 v[88:89], v20, s[10:11] offset:512
	global_load_dwordx2 v[120:121], v28, s[12:13] offset:512
	s_mul_i32 s16, s15, 7
	s_add_i32 s16, s16, s14
	s_cmp_lt_u32 s16, 0x4000
	s_cselect_b32 s16, s16, s14
	v_lshl_add_u32 v21, s16, 10, v1
	s_mul_i32 s17, s16, 0x1800
	v_add_u32_e32 v29, s17, v1
	global_load_dwordx2 v[58:59], v21, s[0:1]
	global_load_dwordx2 v[90:91], v21, s[10:11]
	global_load_dwordx2 v[122:123], v29, s[12:13]
	global_load_dwordx2 v[60:61], v21, s[0:1] offset:512
	global_load_dwordx2 v[92:93], v21, s[10:11] offset:512
	global_load_dwordx2 v[124:125], v29, s[12:13] offset:512
	s_waitcnt vmcnt(42)
	v_lshlrev_b32_e32 v128, 16, v30
	v_and_b32_e32 v129, 0xffff0000, v30
	v_lshlrev_b32_e32 v130, 16, v31
	v_and_b32_e32 v131, 0xffff0000, v31
	v_lshlrev_b32_e32 v136, 16, v62
	v_and_b32_e32 v137, 0xffff0000, v62
	v_lshlrev_b32_e32 v138, 16, v63
	v_and_b32_e32 v139, 0xffff0000, v63
	v_lshlrev_b32_e32 v132, 16, v32
	v_and_b32_e32 v133, 0xffff0000, v32
	v_lshlrev_b32_e32 v134, 16, v33
	v_and_b32_e32 v135, 0xffff0000, v33
	v_lshlrev_b32_e32 v140, 16, v64
	v_and_b32_e32 v141, 0xffff0000, v64
	v_lshlrev_b32_e32 v142, 16, v65
	v_and_b32_e32 v143, 0xffff0000, v65
	v_add_f32_e32 v128, v128, v136
	v_add_f32_e32 v129, v129, v137
	v_add_f32_e32 v130, v130, v138
	v_add_f32_e32 v131, v131, v139
	v_add_f32_e32 v132, v132, v140
	v_add_f32_e32 v133, v133, v141
	v_add_f32_e32 v134, v134, v142
	v_add_f32_e32 v135, v135, v143
	v_mul_f32_e32 v160, v128, v128
	v_fmac_f32_e32 v160, v129, v129
	v_fmac_f32_e32 v160, v130, v130
	v_fmac_f32_e32 v160, v131, v131
	v_mul_f32_e32 v161, v132, v132
	v_fmac_f32_e32 v161, v133, v133
	v_fmac_f32_e32 v161, v134, v134
	v_fmac_f32_e32 v161, v135, v135
	v_lshlrev_b32_e32 v144, 16, v94
	v_and_b32_e32 v145, 0xffff0000, v94
	v_lshlrev_b32_e32 v146, 16, v95
	v_and_b32_e32 v147, 0xffff0000, v95
	v_lshlrev_b32_e32 v148, 16, v96
	v_and_b32_e32 v149, 0xffff0000, v96
	v_lshlrev_b32_e32 v150, 16, v97
	v_and_b32_e32 v151, 0xffff0000, v97
	v_add_f32_dpp v160, v160, v160 quad_perm:[1,0,3,2] row_mask:0xf bank_mask:0xf
	v_add_f32_dpp v161, v161, v161 quad_perm:[1,0,3,2] row_mask:0xf bank_mask:0xf
	v_mul_f32_e32 v152, 0xbfb8aa3b, v144
	v_mul_f32_e32 v153, 0xbfb8aa3b, v145
	v_add_f32_dpp v160, v160, v160 quad_perm:[2,3,0,1] row_mask:0xf bank_mask:0xf
	v_add_f32_dpp v161, v161, v161 quad_perm:[2,3,0,1] row_mask:0xf bank_mask:0xf
	v_mul_f32_e32 v154, 0xbfb8aa3b, v146
	v_mul_f32_e32 v155, 0xbfb8aa3b, v147
	v_add_f32_dpp v160, v160, v160 row_half_mirror row_mask:0xf bank_mask:0xf
	v_add_f32_dpp v161, v161, v161 row_half_mirror row_mask:0xf bank_mask:0xf
	v_mul_f32_e32 v156, 0xbfb8aa3b, v148
	v_mul_f32_e32 v157, 0xbfb8aa3b, v149
	v_add_f32_dpp v160, v160, v160 row_mirror row_mask:0xf bank_mask:0xf
	v_add_f32_dpp v161, v161, v161 row_mirror row_mask:0xf bank_mask:0xf
	v_mul_f32_e32 v158, 0xbfb8aa3b, v150
	v_mul_f32_e32 v159, 0xbfb8aa3b, v151
	v_mov_b32_e32 v162, v160
	v_mov_b32_e32 v163, v161
	s_nop 1
	v_permlane16_swap_b32_e32 v160, v162
	v_permlane16_swap_b32_e32 v161, v163
	v_add_f32_e32 v160, v160, v162
	v_add_f32_e32 v161, v161, v163
	v_fmamk_f32 v160, v160, 0x3c000000, v2
	v_fmamk_f32 v161, v161, 0x3c000000, v2
	v_rsq_f32_e32 v160, v160
	v_rsq_f32_e32 v161, v161
	v_exp_f32_e32 v152, v152
	v_exp_f32_e32 v153, v153
	v_exp_f32_e32 v154, v154
	v_exp_f32_e32 v155, v155
	v_exp_f32_e32 v156, v156
	v_exp_f32_e32 v157, v157
	v_exp_f32_e32 v158, v158
	v_exp_f32_e32 v159, v159
	v_add_f32_e32 v152, 1.0, v152
	v_add_f32_e32 v153, 1.0, v153
	v_add_f32_e32 v154, 1.0, v154
	v_add_f32_e32 v155, 1.0, v155
	v_add_f32_e32 v156, 1.0, v156
	v_add_f32_e32 v157, 1.0, v157
	v_add_f32_e32 v158, 1.0, v158
	v_add_f32_e32 v159, 1.0, v159
	v_rcp_f32_e32 v152, v152
	v_rcp_f32_e32 v153, v153
	v_rcp_f32_e32 v154, v154
	v_rcp_f32_e32 v155, v155
	v_rcp_f32_e32 v156, v156
	v_rcp_f32_e32 v157, v157
	v_rcp_f32_e32 v158, v158
	v_rcp_f32_e32 v159, v159
	v_mul_f32_e32 v128, v128, v160
	v_mul_f32_e32 v129, v129, v160
	v_mul_f32_e32 v130, v130, v160
	v_mul_f32_e32 v131, v131, v160
	v_mul_f32_e32 v132, v132, v161
	v_mul_f32_e32 v133, v133, v161
	v_mul_f32_e32 v134, v134, v161
	v_mul_f32_e32 v135, v135, v161
	v_mul_f32_e32 v152, v152, v144
	v_mul_f32_e32 v153, v153, v145
	v_mul_f32_e32 v154, v154, v146
	v_mul_f32_e32 v155, v155, v147
	v_mul_f32_e32 v156, v156, v148
	v_mul_f32_e32 v157, v157, v149
	v_mul_f32_e32 v158, v158, v150
	v_mul_f32_e32 v159, v159, v151
	v_mul_f32_e32 v128, v4, v128
	v_mul_f32_e32 v129, v5, v129
	v_mul_f32_e32 v130, v6, v130
	v_mul_f32_e32 v131, v7, v131
	v_mul_f32_e32 v132, v4, v132
	v_mul_f32_e32 v133, v5, v133
	v_mul_f32_e32 v134, v6, v134
	v_mul_f32_e32 v135, v7, v135
	v_mul_f32_e32 v128, v152, v128
	v_mul_f32_e32 v129, v153, v129
	v_mul_f32_e32 v130, v154, v130
	v_mul_f32_e32 v131, v155, v131
	v_mul_f32_e32 v132, v156, v132
	v_mul_f32_e32 v133, v157, v133
	v_mul_f32_e32 v134, v158, v134
	v_mul_f32_e32 v135, v159, v135
	v_cvt_pk_bf16_f32 v62, v128, v129
	v_cvt_pk_bf16_f32 v63, v130, v131
	v_cvt_pk_bf16_f32 v64, v132, v133
	v_cvt_pk_bf16_f32 v65, v134, v135
	global_store_dwordx2 v14, v[62:63], s[10:11]
	global_store_dwordx2 v14, v[64:65], s[10:11] offset:512
	s_mul_i32 s16, s15, 1
	s_add_i32 s16, s16, s14
	s_cmp_lt_u32 s16, 0x4000
	s_cbranch_scc0 .Lpd_skip_L1_1
	s_waitcnt vmcnt(38)
	v_lshlrev_b32_e32 v128, 16, v34
	v_and_b32_e32 v129, 0xffff0000, v34
	v_lshlrev_b32_e32 v130, 16, v35
	v_and_b32_e32 v131, 0xffff0000, v35
	v_lshlrev_b32_e32 v136, 16, v66
	v_and_b32_e32 v137, 0xffff0000, v66
	v_lshlrev_b32_e32 v138, 16, v67
	v_and_b32_e32 v139, 0xffff0000, v67
	v_lshlrev_b32_e32 v132, 16, v36
	v_and_b32_e32 v133, 0xffff0000, v36
	v_lshlrev_b32_e32 v134, 16, v37
	v_and_b32_e32 v135, 0xffff0000, v37
	v_lshlrev_b32_e32 v140, 16, v68
	v_and_b32_e32 v141, 0xffff0000, v68
	v_lshlrev_b32_e32 v142, 16, v69
	v_and_b32_e32 v143, 0xffff0000, v69
	v_add_f32_e32 v128, v128, v136
	v_add_f32_e32 v129, v129, v137
	v_add_f32_e32 v130, v130, v138
	v_add_f32_e32 v131, v131, v139
	v_add_f32_e32 v132, v132, v140
	v_add_f32_e32 v133, v133, v141
	v_add_f32_e32 v134, v134, v142
	v_add_f32_e32 v135, v135, v143
	v_mul_f32_e32 v160, v128, v128
	v_fmac_f32_e32 v160, v129, v129
	v_fmac_f32_e32 v160, v130, v130
	v_fmac_f32_e32 v160, v131, v131
	v_mul_f32_e32 v161, v132, v132
	v_fmac_f32_e32 v161, v133, v133
	v_fmac_f32_e32 v161, v134, v134
	v_fmac_f32_e32 v161, v135, v135
	v_lshlrev_b32_e32 v144, 16, v98
	v_and_b32_e32 v145, 0xffff0000, v98
	v_lshlrev_b32_e32 v146, 16, v99
	v_and_b32_e32 v147, 0xffff0000, v99
	v_lshlrev_b32_e32 v148, 16, v100
	v_and_b32_e32 v149, 0xffff0000, v100
	v_lshlrev_b32_e32 v150, 16, v101
	v_and_b32_e32 v151, 0xffff0000, v101
	v_add_f32_dpp v160, v160, v160 quad_perm:[1,0,3,2] row_mask:0xf bank_mask:0xf
	v_add_f32_dpp v161, v161, v161 quad_perm:[1,0,3,2] row_mask:0xf bank_mask:0xf
	v_mul_f32_e32 v152, 0xbfb8aa3b, v144
	v_mul_f32_e32 v153, 0xbfb8aa3b, v145
	v_add_f32_dpp v160, v160, v160 quad_perm:[2,3,0,1] row_mask:0xf bank_mask:0xf
	v_add_f32_dpp v161, v161, v161 quad_perm:[2,3,0,1] row_mask:0xf bank_mask:0xf
	v_mul_f32_e32 v154, 0xbfb8aa3b, v146
	v_mul_f32_e32 v155, 0xbfb8aa3b, v147
	v_add_f32_dpp v160, v160, v160 row_half_mirror row_mask:0xf bank_mask:0xf
	v_add_f32_dpp v161, v161, v161 row_half_mirror row_mask:0xf bank_mask:0xf
	v_mul_f32_e32 v156, 0xbfb8aa3b, v148
	v_mul_f32_e32 v157, 0xbfb8aa3b, v149
	v_add_f32_dpp v160, v160, v160 row_mirror row_mask:0xf bank_mask:0xf
	v_add_f32_dpp v161, v161, v161 row_mirror row_mask:0xf bank_mask:0xf
	v_mul_f32_e32 v158, 0xbfb8aa3b, v150
	v_mul_f32_e32 v159, 0xbfb8aa3b, v151
	v_mov_b32_e32 v162, v160
	v_mov_b32_e32 v163, v161
	s_nop 1
	v_permlane16_swap_b32_e32 v160, v162
	v_permlane16_swap_b32_e32 v161, v163
	v_add_f32_e32 v160, v160, v162
	v_add_f32_e32 v161, v161, v163
	v_fmamk_f32 v160, v160, 0x3c000000, v2
	v_fmamk_f32 v161, v161, 0x3c000000, v2
	v_rsq_f32_e32 v160, v160
	v_rsq_f32_e32 v161, v161
	v_exp_f32_e32 v152, v152
	v_exp_f32_e32 v153, v153
	v_exp_f32_e32 v154, v154
	v_exp_f32_e32 v155, v155
	v_exp_f32_e32 v156, v156
	v_exp_f32_e32 v157, v157
	v_exp_f32_e32 v158, v158
	v_exp_f32_e32 v159, v159
	v_add_f32_e32 v152, 1.0, v152
	v_add_f32_e32 v153, 1.0, v153
	v_add_f32_e32 v154, 1.0, v154
	v_add_f32_e32 v155, 1.0, v155
	v_add_f32_e32 v156, 1.0, v156
	v_add_f32_e32 v157, 1.0, v157
	v_add_f32_e32 v158, 1.0, v158
	v_add_f32_e32 v159, 1.0, v159
	v_rcp_f32_e32 v152, v152
	v_rcp_f32_e32 v153, v153
	v_rcp_f32_e32 v154, v154
	v_rcp_f32_e32 v155, v155
	v_rcp_f32_e32 v156, v156
	v_rcp_f32_e32 v157, v157
	v_rcp_f32_e32 v158, v158
	v_rcp_f32_e32 v159, v159
	v_mul_f32_e32 v128, v128, v160
	v_mul_f32_e32 v129, v129, v160
	v_mul_f32_e32 v130, v130, v160
	v_mul_f32_e32 v131, v131, v160
	v_mul_f32_e32 v132, v132, v161
	v_mul_f32_e32 v133, v133, v161
	v_mul_f32_e32 v134, v134, v161
	v_mul_f32_e32 v135, v135, v161
	v_mul_f32_e32 v152, v152, v144
	v_mul_f32_e32 v153, v153, v145
	v_mul_f32_e32 v154, v154, v146
	v_mul_f32_e32 v155, v155, v147
	v_mul_f32_e32 v156, v156, v148
	v_mul_f32_e32 v157, v157, v149
	v_mul_f32_e32 v158, v158, v150
	v_mul_f32_e32 v159, v159, v151
	v_mul_f32_e32 v128, v4, v128
	v_mul_f32_e32 v129, v5, v129
	v_mul_f32_e32 v130, v6, v130
	v_mul_f32_e32 v131, v7, v131
	v_mul_f32_e32 v132, v4, v132
	v_mul_f32_e32 v133, v5, v133
	v_mul_f32_e32 v134, v6, v134
	v_mul_f32_e32 v135, v7, v135
	v_mul_f32_e32 v128, v152, v128
	v_mul_f32_e32 v129, v153, v129
	v_mul_f32_e32 v130, v154, v130
	v_mul_f32_e32 v131, v155, v131
	v_mul_f32_e32 v132, v156, v132
	v_mul_f32_e32 v133, v157, v133
	v_mul_f32_e32 v134, v158, v134
	v_mul_f32_e32 v135, v159, v135
	v_cvt_pk_bf16_f32 v66, v128, v129
	v_cvt_pk_bf16_f32 v67, v130, v131
	v_cvt_pk_bf16_f32 v68, v132, v133
	v_cvt_pk_bf16_f32 v69, v134, v135
	global_store_dwordx2 v15, v[66:67], s[10:11]
	global_store_dwordx2 v15, v[68:69], s[10:11] offset:512
.Lpd_skip_L1_1:
	s_mul_i32 s16, s15, 2
	s_add_i32 s16, s16, s14
	s_cmp_lt_u32 s16, 0x4000
	s_cbranch_scc0 .Lpd_skip_L1_2
	s_waitcnt vmcnt(34)
	v_lshlrev_b32_e32 v128, 16, v38
	v_and_b32_e32 v129, 0xffff0000, v38
	v_lshlrev_b32_e32 v130, 16, v39
	v_and_b32_e32 v131, 0xffff0000, v39
	v_lshlrev_b32_e32 v136, 16, v70
	v_and_b32_e32 v137, 0xffff0000, v70
	v_lshlrev_b32_e32 v138, 16, v71
	v_and_b32_e32 v139, 0xffff0000, v71
	v_lshlrev_b32_e32 v132, 16, v40
	v_and_b32_e32 v133, 0xffff0000, v40
	v_lshlrev_b32_e32 v134, 16, v41
	v_and_b32_e32 v135, 0xffff0000, v41
	v_lshlrev_b32_e32 v140, 16, v72
	v_and_b32_e32 v141, 0xffff0000, v72
	v_lshlrev_b32_e32 v142, 16, v73
	v_and_b32_e32 v143, 0xffff0000, v73
	v_add_f32_e32 v128, v128, v136
	v_add_f32_e32 v129, v129, v137
	v_add_f32_e32 v130, v130, v138
	v_add_f32_e32 v131, v131, v139
	v_add_f32_e32 v132, v132, v140
	v_add_f32_e32 v133, v133, v141
	v_add_f32_e32 v134, v134, v142
	v_add_f32_e32 v135, v135, v143
	v_mul_f32_e32 v160, v128, v128
	v_fmac_f32_e32 v160, v129, v129
	v_fmac_f32_e32 v160, v130, v130
	v_fmac_f32_e32 v160, v131, v131
	v_mul_f32_e32 v161, v132, v132
	v_fmac_f32_e32 v161, v133, v133
	v_fmac_f32_e32 v161, v134, v134
	v_fmac_f32_e32 v161, v135, v135
	v_lshlrev_b32_e32 v144, 16, v102
	v_and_b32_e32 v145, 0xffff0000, v102
	v_lshlrev_b32_e32 v146, 16, v103
	v_and_b32_e32 v147, 0xffff0000, v103
	v_lshlrev_b32_e32 v148, 16, v104
	v_and_b32_e32 v149, 0xffff0000, v104
	v_lshlrev_b32_e32 v150, 16, v105
	v_and_b32_e32 v151, 0xffff0000, v105
	v_add_f32_dpp v160, v160, v160 quad_perm:[1,0,3,2] row_mask:0xf bank_mask:0xf
	v_add_f32_dpp v161, v161, v161 quad_perm:[1,0,3,2] row_mask:0xf bank_mask:0xf
	v_mul_f32_e32 v152, 0xbfb8aa3b, v144
	v_mul_f32_e32 v153, 0xbfb8aa3b, v145
	v_add_f32_dpp v160, v160, v160 quad_perm:[2,3,0,1] row_mask:0xf bank_mask:0xf
	v_add_f32_dpp v161, v161, v161 quad_perm:[2,3,0,1] row_mask:0xf bank_mask:0xf
	v_mul_f32_e32 v154, 0xbfb8aa3b, v146
	v_mul_f32_e32 v155, 0xbfb8aa3b, v147
	v_add_f32_dpp v160, v160, v160 row_half_mirror row_mask:0xf bank_mask:0xf
	v_add_f32_dpp v161, v161, v161 row_half_mirror row_mask:0xf bank_mask:0xf
	v_mul_f32_e32 v156, 0xbfb8aa3b, v148
	v_mul_f32_e32 v157, 0xbfb8aa3b, v149
	v_add_f32_dpp v160, v160, v160 row_mirror row_mask:0xf bank_mask:0xf
	v_add_f32_dpp v161, v161, v161 row_mirror row_mask:0xf bank_mask:0xf
	v_mul_f32_e32 v158, 0xbfb8aa3b, v150
	v_mul_f32_e32 v159, 0xbfb8aa3b, v151
	v_mov_b32_e32 v162, v160
	v_mov_b32_e32 v163, v161
	s_nop 1
	v_permlane16_swap_b32_e32 v160, v162
	v_permlane16_swap_b32_e32 v161, v163
	v_add_f32_e32 v160, v160, v162
	v_add_f32_e32 v161, v161, v163
	v_fmamk_f32 v160, v160, 0x3c000000, v2
	v_fmamk_f32 v161, v161, 0x3c000000, v2
	v_rsq_f32_e32 v160, v160
	v_rsq_f32_e32 v161, v161
	v_exp_f32_e32 v152, v152
	v_exp_f32_e32 v153, v153
	v_exp_f32_e32 v154, v154
	v_exp_f32_e32 v155, v155
	v_exp_f32_e32 v156, v156
	v_exp_f32_e32 v157, v157
	v_exp_f32_e32 v158, v158
	v_exp_f32_e32 v159, v159
	v_add_f32_e32 v152, 1.0, v152
	v_add_f32_e32 v153, 1.0, v153
	v_add_f32_e32 v154, 1.0, v154
	v_add_f32_e32 v155, 1.0, v155
	v_add_f32_e32 v156, 1.0, v156
	v_add_f32_e32 v157, 1.0, v157
	v_add_f32_e32 v158, 1.0, v158
	v_add_f32_e32 v159, 1.0, v159
	v_rcp_f32_e32 v152, v152
	v_rcp_f32_e32 v153, v153
	v_rcp_f32_e32 v154, v154
	v_rcp_f32_e32 v155, v155
	v_rcp_f32_e32 v156, v156
	v_rcp_f32_e32 v157, v157
	v_rcp_f32_e32 v158, v158
	v_rcp_f32_e32 v159, v159
	v_mul_f32_e32 v128, v128, v160
	v_mul_f32_e32 v129, v129, v160
	v_mul_f32_e32 v130, v130, v160
	v_mul_f32_e32 v131, v131, v160
	v_mul_f32_e32 v132, v132, v161
	v_mul_f32_e32 v133, v133, v161
	v_mul_f32_e32 v134, v134, v161
	v_mul_f32_e32 v135, v135, v161
	v_mul_f32_e32 v152, v152, v144
	v_mul_f32_e32 v153, v153, v145
	v_mul_f32_e32 v154, v154, v146
	v_mul_f32_e32 v155, v155, v147
	v_mul_f32_e32 v156, v156, v148
	v_mul_f32_e32 v157, v157, v149
	v_mul_f32_e32 v158, v158, v150
	v_mul_f32_e32 v159, v159, v151
	v_mul_f32_e32 v128, v4, v128
	v_mul_f32_e32 v129, v5, v129
	v_mul_f32_e32 v130, v6, v130
	v_mul_f32_e32 v131, v7, v131
	v_mul_f32_e32 v132, v4, v132
	v_mul_f32_e32 v133, v5, v133
	v_mul_f32_e32 v134, v6, v134
	v_mul_f32_e32 v135, v7, v135
	v_mul_f32_e32 v128, v152, v128
	v_mul_f32_e32 v129, v153, v129
	v_mul_f32_e32 v130, v154, v130
	v_mul_f32_e32 v131, v155, v131
	v_mul_f32_e32 v132, v156, v132
	v_mul_f32_e32 v133, v157, v133
	v_mul_f32_e32 v134, v158, v134
	v_mul_f32_e32 v135, v159, v135
	v_cvt_pk_bf16_f32 v70, v128, v129
	v_cvt_pk_bf16_f32 v71, v130, v131
	v_cvt_pk_bf16_f32 v72, v132, v133
	v_cvt_pk_bf16_f32 v73, v134, v135
	global_store_dwordx2 v16, v[70:71], s[10:11]
	global_store_dwordx2 v16, v[72:73], s[10:11] offset:512
.Lpd_skip_L1_2:
	s_mul_i32 s16, s15, 3
	s_add_i32 s16, s16, s14
	s_cmp_lt_u32 s16, 0x4000
	s_cbranch_scc0 .Lpd_skip_L1_3
	s_waitcnt vmcnt(30)
	v_lshlrev_b32_e32 v128, 16, v42
	v_and_b32_e32 v129, 0xffff0000, v42
	v_lshlrev_b32_e32 v130, 16, v43
	v_and_b32_e32 v131, 0xffff0000, v43
	v_lshlrev_b32_e32 v136, 16, v74
	v_and_b32_e32 v137, 0xffff0000, v74
	v_lshlrev_b32_e32 v138, 16, v75
	v_and_b32_e32 v139, 0xffff0000, v75
	v_lshlrev_b32_e32 v132, 16, v44
	v_and_b32_e32 v133, 0xffff0000, v44
	v_lshlrev_b32_e32 v134, 16, v45
	v_and_b32_e32 v135, 0xffff0000, v45
	v_lshlrev_b32_e32 v140, 16, v76
	v_and_b32_e32 v141, 0xffff0000, v76
	v_lshlrev_b32_e32 v142, 16, v77
	v_and_b32_e32 v143, 0xffff0000, v77
	v_add_f32_e32 v128, v128, v136
	v_add_f32_e32 v129, v129, v137
	v_add_f32_e32 v130, v130, v138
	v_add_f32_e32 v131, v131, v139
	v_add_f32_e32 v132, v132, v140
	v_add_f32_e32 v133, v133, v141
	v_add_f32_e32 v134, v134, v142
	v_add_f32_e32 v135, v135, v143
	v_mul_f32_e32 v160, v128, v128
	v_fmac_f32_e32 v160, v129, v129
	v_fmac_f32_e32 v160, v130, v130
	v_fmac_f32_e32 v160, v131, v131
	v_mul_f32_e32 v161, v132, v132
	v_fmac_f32_e32 v161, v133, v133
	v_fmac_f32_e32 v161, v134, v134
	v_fmac_f32_e32 v161, v135, v135
	v_lshlrev_b32_e32 v144, 16, v106
	v_and_b32_e32 v145, 0xffff0000, v106
	v_lshlrev_b32_e32 v146, 16, v107
	v_and_b32_e32 v147, 0xffff0000, v107
	v_lshlrev_b32_e32 v148, 16, v108
	v_and_b32_e32 v149, 0xffff0000, v108
	v_lshlrev_b32_e32 v150, 16, v109
	v_and_b32_e32 v151, 0xffff0000, v109
	v_add_f32_dpp v160, v160, v160 quad_perm:[1,0,3,2] row_mask:0xf bank_mask:0xf
	v_add_f32_dpp v161, v161, v161 quad_perm:[1,0,3,2] row_mask:0xf bank_mask:0xf
	v_mul_f32_e32 v152, 0xbfb8aa3b, v144
	v_mul_f32_e32 v153, 0xbfb8aa3b, v145
	v_add_f32_dpp v160, v160, v160 quad_perm:[2,3,0,1] row_mask:0xf bank_mask:0xf
	v_add_f32_dpp v161, v161, v161 quad_perm:[2,3,0,1] row_mask:0xf bank_mask:0xf
	v_mul_f32_e32 v154, 0xbfb8aa3b, v146
	v_mul_f32_e32 v155, 0xbfb8aa3b, v147
	v_add_f32_dpp v160, v160, v160 row_half_mirror row_mask:0xf bank_mask:0xf
	v_add_f32_dpp v161, v161, v161 row_half_mirror row_mask:0xf bank_mask:0xf
	v_mul_f32_e32 v156, 0xbfb8aa3b, v148
	v_mul_f32_e32 v157, 0xbfb8aa3b, v149
	v_add_f32_dpp v160, v160, v160 row_mirror row_mask:0xf bank_mask:0xf
	v_add_f32_dpp v161, v161, v161 row_mirror row_mask:0xf bank_mask:0xf
	v_mul_f32_e32 v158, 0xbfb8aa3b, v150
	v_mul_f32_e32 v159, 0xbfb8aa3b, v151
	v_mov_b32_e32 v162, v160
	v_mov_b32_e32 v163, v161
	s_nop 1
	v_permlane16_swap_b32_e32 v160, v162
	v_permlane16_swap_b32_e32 v161, v163
	v_add_f32_e32 v160, v160, v162
	v_add_f32_e32 v161, v161, v163
	v_fmamk_f32 v160, v160, 0x3c000000, v2
	v_fmamk_f32 v161, v161, 0x3c000000, v2
	v_rsq_f32_e32 v160, v160
	v_rsq_f32_e32 v161, v161
	v_exp_f32_e32 v152, v152
	v_exp_f32_e32 v153, v153
	v_exp_f32_e32 v154, v154
	v_exp_f32_e32 v155, v155
	v_exp_f32_e32 v156, v156
	v_exp_f32_e32 v157, v157
	v_exp_f32_e32 v158, v158
	v_exp_f32_e32 v159, v159
	v_add_f32_e32 v152, 1.0, v152
	v_add_f32_e32 v153, 1.0, v153
	v_add_f32_e32 v154, 1.0, v154
	v_add_f32_e32 v155, 1.0, v155
	v_add_f32_e32 v156, 1.0, v156
	v_add_f32_e32 v157, 1.0, v157
	v_add_f32_e32 v158, 1.0, v158
	v_add_f32_e32 v159, 1.0, v159
	v_rcp_f32_e32 v152, v152
	v_rcp_f32_e32 v153, v153
	v_rcp_f32_e32 v154, v154
	v_rcp_f32_e32 v155, v155
	v_rcp_f32_e32 v156, v156
	v_rcp_f32_e32 v157, v157
	v_rcp_f32_e32 v158, v158
	v_rcp_f32_e32 v159, v159
	v_mul_f32_e32 v128, v128, v160
	v_mul_f32_e32 v129, v129, v160
	v_mul_f32_e32 v130, v130, v160
	v_mul_f32_e32 v131, v131, v160
	v_mul_f32_e32 v132, v132, v161
	v_mul_f32_e32 v133, v133, v161
	v_mul_f32_e32 v134, v134, v161
	v_mul_f32_e32 v135, v135, v161
	v_mul_f32_e32 v152, v152, v144
	v_mul_f32_e32 v153, v153, v145
	v_mul_f32_e32 v154, v154, v146
	v_mul_f32_e32 v155, v155, v147
	v_mul_f32_e32 v156, v156, v148
	v_mul_f32_e32 v157, v157, v149
	v_mul_f32_e32 v158, v158, v150
	v_mul_f32_e32 v159, v159, v151
	v_mul_f32_e32 v128, v4, v128
	v_mul_f32_e32 v129, v5, v129
	v_mul_f32_e32 v130, v6, v130
	v_mul_f32_e32 v131, v7, v131
	v_mul_f32_e32 v132, v4, v132
	v_mul_f32_e32 v133, v5, v133
	v_mul_f32_e32 v134, v6, v134
	v_mul_f32_e32 v135, v7, v135
	v_mul_f32_e32 v128, v152, v128
	v_mul_f32_e32 v129, v153, v129
	v_mul_f32_e32 v130, v154, v130
	v_mul_f32_e32 v131, v155, v131
	v_mul_f32_e32 v132, v156, v132
	v_mul_f32_e32 v133, v157, v133
	v_mul_f32_e32 v134, v158, v134
	v_mul_f32_e32 v135, v159, v135
	v_cvt_pk_bf16_f32 v74, v128, v129
	v_cvt_pk_bf16_f32 v75, v130, v131
	v_cvt_pk_bf16_f32 v76, v132, v133
	v_cvt_pk_bf16_f32 v77, v134, v135
	global_store_dwordx2 v17, v[74:75], s[10:11]
	global_store_dwordx2 v17, v[76:77], s[10:11] offset:512
.Lpd_skip_L1_3:
	s_mul_i32 s16, s15, 4
	s_add_i32 s16, s16, s14
	s_cmp_lt_u32 s16, 0x4000
	s_cbranch_scc0 .Lpd_skip_L1_4
	s_waitcnt vmcnt(26)
	v_lshlrev_b32_e32 v128, 16, v46
	v_and_b32_e32 v129, 0xffff0000, v46
	v_lshlrev_b32_e32 v130, 16, v47
	v_and_b32_e32 v131, 0xffff0000, v47
	v_lshlrev_b32_e32 v136, 16, v78
	v_and_b32_e32 v137, 0xffff0000, v78
	v_lshlrev_b32_e32 v138, 16, v79
	v_and_b32_e32 v139, 0xffff0000, v79
	v_lshlrev_b32_e32 v132, 16, v48
	v_and_b32_e32 v133, 0xffff0000, v48
	v_lshlrev_b32_e32 v134, 16, v49
	v_and_b32_e32 v135, 0xffff0000, v49
	v_lshlrev_b32_e32 v140, 16, v80
	v_and_b32_e32 v141, 0xffff0000, v80
	v_lshlrev_b32_e32 v142, 16, v81
	v_and_b32_e32 v143, 0xffff0000, v81
	v_add_f32_e32 v128, v128, v136
	v_add_f32_e32 v129, v129, v137
	v_add_f32_e32 v130, v130, v138
	v_add_f32_e32 v131, v131, v139
	v_add_f32_e32 v132, v132, v140
	v_add_f32_e32 v133, v133, v141
	v_add_f32_e32 v134, v134, v142
	v_add_f32_e32 v135, v135, v143
	v_mul_f32_e32 v160, v128, v128
	v_fmac_f32_e32 v160, v129, v129
	v_fmac_f32_e32 v160, v130, v130
	v_fmac_f32_e32 v160, v131, v131
	v_mul_f32_e32 v161, v132, v132
	v_fmac_f32_e32 v161, v133, v133
	v_fmac_f32_e32 v161, v134, v134
	v_fmac_f32_e32 v161, v135, v135
	v_lshlrev_b32_e32 v144, 16, v110
	v_and_b32_e32 v145, 0xffff0000, v110
	v_lshlrev_b32_e32 v146, 16, v111
	v_and_b32_e32 v147, 0xffff0000, v111
	v_lshlrev_b32_e32 v148, 16, v112
	v_and_b32_e32 v149, 0xffff0000, v112
	v_lshlrev_b32_e32 v150, 16, v113
	v_and_b32_e32 v151, 0xffff0000, v113
	v_add_f32_dpp v160, v160, v160 quad_perm:[1,0,3,2] row_mask:0xf bank_mask:0xf
	v_add_f32_dpp v161, v161, v161 quad_perm:[1,0,3,2] row_mask:0xf bank_mask:0xf
	v_mul_f32_e32 v152, 0xbfb8aa3b, v144
	v_mul_f32_e32 v153, 0xbfb8aa3b, v145
	v_add_f32_dpp v160, v160, v160 quad_perm:[2,3,0,1] row_mask:0xf bank_mask:0xf
	v_add_f32_dpp v161, v161, v161 quad_perm:[2,3,0,1] row_mask:0xf bank_mask:0xf
	v_mul_f32_e32 v154, 0xbfb8aa3b, v146
	v_mul_f32_e32 v155, 0xbfb8aa3b, v147
	v_add_f32_dpp v160, v160, v160 row_half_mirror row_mask:0xf bank_mask:0xf
	v_add_f32_dpp v161, v161, v161 row_half_mirror row_mask:0xf bank_mask:0xf
	v_mul_f32_e32 v156, 0xbfb8aa3b, v148
	v_mul_f32_e32 v157, 0xbfb8aa3b, v149
	v_add_f32_dpp v160, v160, v160 row_mirror row_mask:0xf bank_mask:0xf
	v_add_f32_dpp v161, v161, v161 row_mirror row_mask:0xf bank_mask:0xf
	v_mul_f32_e32 v158, 0xbfb8aa3b, v150
	v_mul_f32_e32 v159, 0xbfb8aa3b, v151
	v_mov_b32_e32 v162, v160
	v_mov_b32_e32 v163, v161
	s_nop 1
	v_permlane16_swap_b32_e32 v160, v162
	v_permlane16_swap_b32_e32 v161, v163
	v_add_f32_e32 v160, v160, v162
	v_add_f32_e32 v161, v161, v163
	v_fmamk_f32 v160, v160, 0x3c000000, v2
	v_fmamk_f32 v161, v161, 0x3c000000, v2
	v_rsq_f32_e32 v160, v160
	v_rsq_f32_e32 v161, v161
	v_exp_f32_e32 v152, v152
	v_exp_f32_e32 v153, v153
	v_exp_f32_e32 v154, v154
	v_exp_f32_e32 v155, v155
	v_exp_f32_e32 v156, v156
	v_exp_f32_e32 v157, v157
	v_exp_f32_e32 v158, v158
	v_exp_f32_e32 v159, v159
	v_add_f32_e32 v152, 1.0, v152
	v_add_f32_e32 v153, 1.0, v153
	v_add_f32_e32 v154, 1.0, v154
	v_add_f32_e32 v155, 1.0, v155
	v_add_f32_e32 v156, 1.0, v156
	v_add_f32_e32 v157, 1.0, v157
	v_add_f32_e32 v158, 1.0, v158
	v_add_f32_e32 v159, 1.0, v159
	v_rcp_f32_e32 v152, v152
	v_rcp_f32_e32 v153, v153
	v_rcp_f32_e32 v154, v154
	v_rcp_f32_e32 v155, v155
	v_rcp_f32_e32 v156, v156
	v_rcp_f32_e32 v157, v157
	v_rcp_f32_e32 v158, v158
	v_rcp_f32_e32 v159, v159
	v_mul_f32_e32 v128, v128, v160
	v_mul_f32_e32 v129, v129, v160
	v_mul_f32_e32 v130, v130, v160
	v_mul_f32_e32 v131, v131, v160
	v_mul_f32_e32 v132, v132, v161
	v_mul_f32_e32 v133, v133, v161
	v_mul_f32_e32 v134, v134, v161
	v_mul_f32_e32 v135, v135, v161
	v_mul_f32_e32 v152, v152, v144
	v_mul_f32_e32 v153, v153, v145
	v_mul_f32_e32 v154, v154, v146
	v_mul_f32_e32 v155, v155, v147
	v_mul_f32_e32 v156, v156, v148
	v_mul_f32_e32 v157, v157, v149
	v_mul_f32_e32 v158, v158, v150
	v_mul_f32_e32 v159, v159, v151
	v_mul_f32_e32 v128, v4, v128
	v_mul_f32_e32 v129, v5, v129
	v_mul_f32_e32 v130, v6, v130
	v_mul_f32_e32 v131, v7, v131
	v_mul_f32_e32 v132, v4, v132
	v_mul_f32_e32 v133, v5, v133
	v_mul_f32_e32 v134, v6, v134
	v_mul_f32_e32 v135, v7, v135
	v_mul_f32_e32 v128, v152, v128
	v_mul_f32_e32 v129, v153, v129
	v_mul_f32_e32 v130, v154, v130
	v_mul_f32_e32 v131, v155, v131
	v_mul_f32_e32 v132, v156, v132
	v_mul_f32_e32 v133, v157, v133
	v_mul_f32_e32 v134, v158, v134
	v_mul_f32_e32 v135, v159, v135
	v_cvt_pk_bf16_f32 v78, v128, v129
	v_cvt_pk_bf16_f32 v79, v130, v131
	v_cvt_pk_bf16_f32 v80, v132, v133
	v_cvt_pk_bf16_f32 v81, v134, v135
	global_store_dwordx2 v18, v[78:79], s[10:11]
	global_store_dwordx2 v18, v[80:81], s[10:11] offset:512
.Lpd_skip_L1_4:
	s_mul_i32 s16, s15, 5
	s_add_i32 s16, s16, s14
	s_cmp_lt_u32 s16, 0x4000
	s_cbranch_scc0 .Lpd_skip_L1_5
	s_waitcnt vmcnt(22)
	v_lshlrev_b32_e32 v128, 16, v50
	v_and_b32_e32 v129, 0xffff0000, v50
	v_lshlrev_b32_e32 v130, 16, v51
	v_and_b32_e32 v131, 0xffff0000, v51
	v_lshlrev_b32_e32 v136, 16, v82
	v_and_b32_e32 v137, 0xffff0000, v82
	v_lshlrev_b32_e32 v138, 16, v83
	v_and_b32_e32 v139, 0xffff0000, v83
	v_lshlrev_b32_e32 v132, 16, v52
	v_and_b32_e32 v133, 0xffff0000, v52
	v_lshlrev_b32_e32 v134, 16, v53
	v_and_b32_e32 v135, 0xffff0000, v53
	v_lshlrev_b32_e32 v140, 16, v84
	v_and_b32_e32 v141, 0xffff0000, v84
	v_lshlrev_b32_e32 v142, 16, v85
	v_and_b32_e32 v143, 0xffff0000, v85
	v_add_f32_e32 v128, v128, v136
	v_add_f32_e32 v129, v129, v137
	v_add_f32_e32 v130, v130, v138
	v_add_f32_e32 v131, v131, v139
	v_add_f32_e32 v132, v132, v140
	v_add_f32_e32 v133, v133, v141
	v_add_f32_e32 v134, v134, v142
	v_add_f32_e32 v135, v135, v143
	v_mul_f32_e32 v160, v128, v128
	v_fmac_f32_e32 v160, v129, v129
	v_fmac_f32_e32 v160, v130, v130
	v_fmac_f32_e32 v160, v131, v131
	v_mul_f32_e32 v161, v132, v132
	v_fmac_f32_e32 v161, v133, v133
	v_fmac_f32_e32 v161, v134, v134
	v_fmac_f32_e32 v161, v135, v135
	v_lshlrev_b32_e32 v144, 16, v114
	v_and_b32_e32 v145, 0xffff0000, v114
	v_lshlrev_b32_e32 v146, 16, v115
	v_and_b32_e32 v147, 0xffff0000, v115
	v_lshlrev_b32_e32 v148, 16, v116
	v_and_b32_e32 v149, 0xffff0000, v116
	v_lshlrev_b32_e32 v150, 16, v117
	v_and_b32_e32 v151, 0xffff0000, v117
	v_add_f32_dpp v160, v160, v160 quad_perm:[1,0,3,2] row_mask:0xf bank_mask:0xf
	v_add_f32_dpp v161, v161, v161 quad_perm:[1,0,3,2] row_mask:0xf bank_mask:0xf
	v_mul_f32_e32 v152, 0xbfb8aa3b, v144
	v_mul_f32_e32 v153, 0xbfb8aa3b, v145
	v_add_f32_dpp v160, v160, v160 quad_perm:[2,3,0,1] row_mask:0xf bank_mask:0xf
	v_add_f32_dpp v161, v161, v161 quad_perm:[2,3,0,1] row_mask:0xf bank_mask:0xf
	v_mul_f32_e32 v154, 0xbfb8aa3b, v146
	v_mul_f32_e32 v155, 0xbfb8aa3b, v147
	v_add_f32_dpp v160, v160, v160 row_half_mirror row_mask:0xf bank_mask:0xf
	v_add_f32_dpp v161, v161, v161 row_half_mirror row_mask:0xf bank_mask:0xf
	v_mul_f32_e32 v156, 0xbfb8aa3b, v148
	v_mul_f32_e32 v157, 0xbfb8aa3b, v149
	v_add_f32_dpp v160, v160, v160 row_mirror row_mask:0xf bank_mask:0xf
	v_add_f32_dpp v161, v161, v161 row_mirror row_mask:0xf bank_mask:0xf
	v_mul_f32_e32 v158, 0xbfb8aa3b, v150
	v_mul_f32_e32 v159, 0xbfb8aa3b, v151
	v_mov_b32_e32 v162, v160
	v_mov_b32_e32 v163, v161
	s_nop 1
	v_permlane16_swap_b32_e32 v160, v162
	v_permlane16_swap_b32_e32 v161, v163
	v_add_f32_e32 v160, v160, v162
	v_add_f32_e32 v161, v161, v163
	v_fmamk_f32 v160, v160, 0x3c000000, v2
	v_fmamk_f32 v161, v161, 0x3c000000, v2
	v_rsq_f32_e32 v160, v160
	v_rsq_f32_e32 v161, v161
	v_exp_f32_e32 v152, v152
	v_exp_f32_e32 v153, v153
	v_exp_f32_e32 v154, v154
	v_exp_f32_e32 v155, v155
	v_exp_f32_e32 v156, v156
	v_exp_f32_e32 v157, v157
	v_exp_f32_e32 v158, v158
	v_exp_f32_e32 v159, v159
	v_add_f32_e32 v152, 1.0, v152
	v_add_f32_e32 v153, 1.0, v153
	v_add_f32_e32 v154, 1.0, v154
	v_add_f32_e32 v155, 1.0, v155
	v_add_f32_e32 v156, 1.0, v156
	v_add_f32_e32 v157, 1.0, v157
	v_add_f32_e32 v158, 1.0, v158
	v_add_f32_e32 v159, 1.0, v159
	v_rcp_f32_e32 v152, v152
	v_rcp_f32_e32 v153, v153
	v_rcp_f32_e32 v154, v154
	v_rcp_f32_e32 v155, v155
	v_rcp_f32_e32 v156, v156
	v_rcp_f32_e32 v157, v157
	v_rcp_f32_e32 v158, v158
	v_rcp_f32_e32 v159, v159
	v_mul_f32_e32 v128, v128, v160
	v_mul_f32_e32 v129, v129, v160
	v_mul_f32_e32 v130, v130, v160
	v_mul_f32_e32 v131, v131, v160
	v_mul_f32_e32 v132, v132, v161
	v_mul_f32_e32 v133, v133, v161
	v_mul_f32_e32 v134, v134, v161
	v_mul_f32_e32 v135, v135, v161
	v_mul_f32_e32 v152, v152, v144
	v_mul_f32_e32 v153, v153, v145
	v_mul_f32_e32 v154, v154, v146
	v_mul_f32_e32 v155, v155, v147
	v_mul_f32_e32 v156, v156, v148
	v_mul_f32_e32 v157, v157, v149
	v_mul_f32_e32 v158, v158, v150
	v_mul_f32_e32 v159, v159, v151
	v_mul_f32_e32 v128, v4, v128
	v_mul_f32_e32 v129, v5, v129
	v_mul_f32_e32 v130, v6, v130
	v_mul_f32_e32 v131, v7, v131
	v_mul_f32_e32 v132, v4, v132
	v_mul_f32_e32 v133, v5, v133
	v_mul_f32_e32 v134, v6, v134
	v_mul_f32_e32 v135, v7, v135
	v_mul_f32_e32 v128, v152, v128
	v_mul_f32_e32 v129, v153, v129
	v_mul_f32_e32 v130, v154, v130
	v_mul_f32_e32 v131, v155, v131
	v_mul_f32_e32 v132, v156, v132
	v_mul_f32_e32 v133, v157, v133
	v_mul_f32_e32 v134, v158, v134
	v_mul_f32_e32 v135, v159, v135
	v_cvt_pk_bf16_f32 v82, v128, v129
	v_cvt_pk_bf16_f32 v83, v130, v131
	v_cvt_pk_bf16_f32 v84, v132, v133
	v_cvt_pk_bf16_f32 v85, v134, v135
	global_store_dwordx2 v19, v[82:83], s[10:11]
	global_store_dwordx2 v19, v[84:85], s[10:11] offset:512
.Lpd_skip_L1_5:
	s_mul_i32 s16, s15, 6
	s_add_i32 s16, s16, s14
	s_cmp_lt_u32 s16, 0x4000
	s_cbranch_scc0 .Lpd_skip_L1_6
	s_waitcnt vmcnt(18)
	v_lshlrev_b32_e32 v128, 16, v54
	v_and_b32_e32 v129, 0xffff0000, v54
	v_lshlrev_b32_e32 v130, 16, v55
	v_and_b32_e32 v131, 0xffff0000, v55
	v_lshlrev_b32_e32 v136, 16, v86
	v_and_b32_e32 v137, 0xffff0000, v86
	v_lshlrev_b32_e32 v138, 16, v87
	v_and_b32_e32 v139, 0xffff0000, v87
	v_lshlrev_b32_e32 v132, 16, v56
	v_and_b32_e32 v133, 0xffff0000, v56
	v_lshlrev_b32_e32 v134, 16, v57
	v_and_b32_e32 v135, 0xffff0000, v57
	v_lshlrev_b32_e32 v140, 16, v88
	v_and_b32_e32 v141, 0xffff0000, v88
	v_lshlrev_b32_e32 v142, 16, v89
	v_and_b32_e32 v143, 0xffff0000, v89
	v_add_f32_e32 v128, v128, v136
	v_add_f32_e32 v129, v129, v137
	v_add_f32_e32 v130, v130, v138
	v_add_f32_e32 v131, v131, v139
	v_add_f32_e32 v132, v132, v140
	v_add_f32_e32 v133, v133, v141
	v_add_f32_e32 v134, v134, v142
	v_add_f32_e32 v135, v135, v143
	v_mul_f32_e32 v160, v128, v128
	v_fmac_f32_e32 v160, v129, v129
	v_fmac_f32_e32 v160, v130, v130
	v_fmac_f32_e32 v160, v131, v131
	v_mul_f32_e32 v161, v132, v132
	v_fmac_f32_e32 v161, v133, v133
	v_fmac_f32_e32 v161, v134, v134
	v_fmac_f32_e32 v161, v135, v135
	v_lshlrev_b32_e32 v144, 16, v118
	v_and_b32_e32 v145, 0xffff0000, v118
	v_lshlrev_b32_e32 v146, 16, v119
	v_and_b32_e32 v147, 0xffff0000, v119
	v_lshlrev_b32_e32 v148, 16, v120
	v_and_b32_e32 v149, 0xffff0000, v120
	v_lshlrev_b32_e32 v150, 16, v121
	v_and_b32_e32 v151, 0xffff0000, v121
	v_add_f32_dpp v160, v160, v160 quad_perm:[1,0,3,2] row_mask:0xf bank_mask:0xf
	v_add_f32_dpp v161, v161, v161 quad_perm:[1,0,3,2] row_mask:0xf bank_mask:0xf
	v_mul_f32_e32 v152, 0xbfb8aa3b, v144
	v_mul_f32_e32 v153, 0xbfb8aa3b, v145
	v_add_f32_dpp v160, v160, v160 quad_perm:[2,3,0,1] row_mask:0xf bank_mask:0xf
	v_add_f32_dpp v161, v161, v161 quad_perm:[2,3,0,1] row_mask:0xf bank_mask:0xf
	v_mul_f32_e32 v154, 0xbfb8aa3b, v146
	v_mul_f32_e32 v155, 0xbfb8aa3b, v147
	v_add_f32_dpp v160, v160, v160 row_half_mirror row_mask:0xf bank_mask:0xf
	v_add_f32_dpp v161, v161, v161 row_half_mirror row_mask:0xf bank_mask:0xf
	v_mul_f32_e32 v156, 0xbfb8aa3b, v148
	v_mul_f32_e32 v157, 0xbfb8aa3b, v149
	v_add_f32_dpp v160, v160, v160 row_mirror row_mask:0xf bank_mask:0xf
	v_add_f32_dpp v161, v161, v161 row_mirror row_mask:0xf bank_mask:0xf
	v_mul_f32_e32 v158, 0xbfb8aa3b, v150
	v_mul_f32_e32 v159, 0xbfb8aa3b, v151
	v_mov_b32_e32 v162, v160
	v_mov_b32_e32 v163, v161
	s_nop 1
	v_permlane16_swap_b32_e32 v160, v162
	v_permlane16_swap_b32_e32 v161, v163
	v_add_f32_e32 v160, v160, v162
	v_add_f32_e32 v161, v161, v163
	v_fmamk_f32 v160, v160, 0x3c000000, v2
	v_fmamk_f32 v161, v161, 0x3c000000, v2
	v_rsq_f32_e32 v160, v160
	v_rsq_f32_e32 v161, v161
	v_exp_f32_e32 v152, v152
	v_exp_f32_e32 v153, v153
	v_exp_f32_e32 v154, v154
	v_exp_f32_e32 v155, v155
	v_exp_f32_e32 v156, v156
	v_exp_f32_e32 v157, v157
	v_exp_f32_e32 v158, v158
	v_exp_f32_e32 v159, v159
	v_add_f32_e32 v152, 1.0, v152
	v_add_f32_e32 v153, 1.0, v153
	v_add_f32_e32 v154, 1.0, v154
	v_add_f32_e32 v155, 1.0, v155
	v_add_f32_e32 v156, 1.0, v156
	v_add_f32_e32 v157, 1.0, v157
	v_add_f32_e32 v158, 1.0, v158
	v_add_f32_e32 v159, 1.0, v159
	v_rcp_f32_e32 v152, v152
	v_rcp_f32_e32 v153, v153
	v_rcp_f32_e32 v154, v154
	v_rcp_f32_e32 v155, v155
	v_rcp_f32_e32 v156, v156
	v_rcp_f32_e32 v157, v157
	v_rcp_f32_e32 v158, v158
	v_rcp_f32_e32 v159, v159
	v_mul_f32_e32 v128, v128, v160
	v_mul_f32_e32 v129, v129, v160
	v_mul_f32_e32 v130, v130, v160
	v_mul_f32_e32 v131, v131, v160
	v_mul_f32_e32 v132, v132, v161
	v_mul_f32_e32 v133, v133, v161
	v_mul_f32_e32 v134, v134, v161
	v_mul_f32_e32 v135, v135, v161
	v_mul_f32_e32 v152, v152, v144
	v_mul_f32_e32 v153, v153, v145
	v_mul_f32_e32 v154, v154, v146
	v_mul_f32_e32 v155, v155, v147
	v_mul_f32_e32 v156, v156, v148
	v_mul_f32_e32 v157, v157, v149
	v_mul_f32_e32 v158, v158, v150
	v_mul_f32_e32 v159, v159, v151
	v_mul_f32_e32 v128, v4, v128
	v_mul_f32_e32 v129, v5, v129
	v_mul_f32_e32 v130, v6, v130
	v_mul_f32_e32 v131, v7, v131
	v_mul_f32_e32 v132, v4, v132
	v_mul_f32_e32 v133, v5, v133
	v_mul_f32_e32 v134, v6, v134
	v_mul_f32_e32 v135, v7, v135
	v_mul_f32_e32 v128, v152, v128
	v_mul_f32_e32 v129, v153, v129
	v_mul_f32_e32 v130, v154, v130
	v_mul_f32_e32 v131, v155, v131
	v_mul_f32_e32 v132, v156, v132
	v_mul_f32_e32 v133, v157, v133
	v_mul_f32_e32 v134, v158, v134
	v_mul_f32_e32 v135, v159, v135
	v_cvt_pk_bf16_f32 v86, v128, v129
	v_cvt_pk_bf16_f32 v87, v130, v131
	v_cvt_pk_bf16_f32 v88, v132, v133
	v_cvt_pk_bf16_f32 v89, v134, v135
	global_store_dwordx2 v20, v[86:87], s[10:11]
	global_store_dwordx2 v20, v[88:89], s[10:11] offset:512
.Lpd_skip_L1_6:
	s_mul_i32 s16, s15, 7
	s_add_i32 s16, s16, s14
	s_cmp_lt_u32 s16, 0x4000
	s_cbranch_scc0 .Lpd_skip_L1_7
	s_waitcnt vmcnt(14)
	v_lshlrev_b32_e32 v128, 16, v58
	v_and_b32_e32 v129, 0xffff0000, v58
	v_lshlrev_b32_e32 v130, 16, v59
	v_and_b32_e32 v131, 0xffff0000, v59
	v_lshlrev_b32_e32 v136, 16, v90
	v_and_b32_e32 v137, 0xffff0000, v90
	v_lshlrev_b32_e32 v138, 16, v91
	v_and_b32_e32 v139, 0xffff0000, v91
	v_lshlrev_b32_e32 v132, 16, v60
	v_and_b32_e32 v133, 0xffff0000, v60
	v_lshlrev_b32_e32 v134, 16, v61
	v_and_b32_e32 v135, 0xffff0000, v61
	v_lshlrev_b32_e32 v140, 16, v92
	v_and_b32_e32 v141, 0xffff0000, v92
	v_lshlrev_b32_e32 v142, 16, v93
	v_and_b32_e32 v143, 0xffff0000, v93
	v_add_f32_e32 v128, v128, v136
	v_add_f32_e32 v129, v129, v137
	v_add_f32_e32 v130, v130, v138
	v_add_f32_e32 v131, v131, v139
	v_add_f32_e32 v132, v132, v140
	v_add_f32_e32 v133, v133, v141
	v_add_f32_e32 v134, v134, v142
	v_add_f32_e32 v135, v135, v143
	v_mul_f32_e32 v160, v128, v128
	v_fmac_f32_e32 v160, v129, v129
	v_fmac_f32_e32 v160, v130, v130
	v_fmac_f32_e32 v160, v131, v131
	v_mul_f32_e32 v161, v132, v132
	v_fmac_f32_e32 v161, v133, v133
	v_fmac_f32_e32 v161, v134, v134
	v_fmac_f32_e32 v161, v135, v135
	v_lshlrev_b32_e32 v144, 16, v122
	v_and_b32_e32 v145, 0xffff0000, v122
	v_lshlrev_b32_e32 v146, 16, v123
	v_and_b32_e32 v147, 0xffff0000, v123
	v_lshlrev_b32_e32 v148, 16, v124
	v_and_b32_e32 v149, 0xffff0000, v124
	v_lshlrev_b32_e32 v150, 16, v125
	v_and_b32_e32 v151, 0xffff0000, v125
	v_add_f32_dpp v160, v160, v160 quad_perm:[1,0,3,2] row_mask:0xf bank_mask:0xf
	v_add_f32_dpp v161, v161, v161 quad_perm:[1,0,3,2] row_mask:0xf bank_mask:0xf
	v_mul_f32_e32 v152, 0xbfb8aa3b, v144
	v_mul_f32_e32 v153, 0xbfb8aa3b, v145
	v_add_f32_dpp v160, v160, v160 quad_perm:[2,3,0,1] row_mask:0xf bank_mask:0xf
	v_add_f32_dpp v161, v161, v161 quad_perm:[2,3,0,1] row_mask:0xf bank_mask:0xf
	v_mul_f32_e32 v154, 0xbfb8aa3b, v146
	v_mul_f32_e32 v155, 0xbfb8aa3b, v147
	v_add_f32_dpp v160, v160, v160 row_half_mirror row_mask:0xf bank_mask:0xf
	v_add_f32_dpp v161, v161, v161 row_half_mirror row_mask:0xf bank_mask:0xf
	v_mul_f32_e32 v156, 0xbfb8aa3b, v148
	v_mul_f32_e32 v157, 0xbfb8aa3b, v149
	v_add_f32_dpp v160, v160, v160 row_mirror row_mask:0xf bank_mask:0xf
	v_add_f32_dpp v161, v161, v161 row_mirror row_mask:0xf bank_mask:0xf
	v_mul_f32_e32 v158, 0xbfb8aa3b, v150
	v_mul_f32_e32 v159, 0xbfb8aa3b, v151
	v_mov_b32_e32 v162, v160
	v_mov_b32_e32 v163, v161
	s_nop 1
	v_permlane16_swap_b32_e32 v160, v162
	v_permlane16_swap_b32_e32 v161, v163
	v_add_f32_e32 v160, v160, v162
	v_add_f32_e32 v161, v161, v163
	v_fmamk_f32 v160, v160, 0x3c000000, v2
	v_fmamk_f32 v161, v161, 0x3c000000, v2
	v_rsq_f32_e32 v160, v160
	v_rsq_f32_e32 v161, v161
	v_exp_f32_e32 v152, v152
	v_exp_f32_e32 v153, v153
	v_exp_f32_e32 v154, v154
	v_exp_f32_e32 v155, v155
	v_exp_f32_e32 v156, v156
	v_exp_f32_e32 v157, v157
	v_exp_f32_e32 v158, v158
	v_exp_f32_e32 v159, v159
	v_add_f32_e32 v152, 1.0, v152
	v_add_f32_e32 v153, 1.0, v153
	v_add_f32_e32 v154, 1.0, v154
	v_add_f32_e32 v155, 1.0, v155
	v_add_f32_e32 v156, 1.0, v156
	v_add_f32_e32 v157, 1.0, v157
	v_add_f32_e32 v158, 1.0, v158
	v_add_f32_e32 v159, 1.0, v159
	v_rcp_f32_e32 v152, v152
	v_rcp_f32_e32 v153, v153
	v_rcp_f32_e32 v154, v154
	v_rcp_f32_e32 v155, v155
	v_rcp_f32_e32 v156, v156
	v_rcp_f32_e32 v157, v157
	v_rcp_f32_e32 v158, v158
	v_rcp_f32_e32 v159, v159
	v_mul_f32_e32 v128, v128, v160
	v_mul_f32_e32 v129, v129, v160
	v_mul_f32_e32 v130, v130, v160
	v_mul_f32_e32 v131, v131, v160
	v_mul_f32_e32 v132, v132, v161
	v_mul_f32_e32 v133, v133, v161
	v_mul_f32_e32 v134, v134, v161
	v_mul_f32_e32 v135, v135, v161
	v_mul_f32_e32 v152, v152, v144
	v_mul_f32_e32 v153, v153, v145
	v_mul_f32_e32 v154, v154, v146
	v_mul_f32_e32 v155, v155, v147
	v_mul_f32_e32 v156, v156, v148
	v_mul_f32_e32 v157, v157, v149
	v_mul_f32_e32 v158, v158, v150
	v_mul_f32_e32 v159, v159, v151
	v_mul_f32_e32 v128, v4, v128
	v_mul_f32_e32 v129, v5, v129
	v_mul_f32_e32 v130, v6, v130
	v_mul_f32_e32 v131, v7, v131
	v_mul_f32_e32 v132, v4, v132
	v_mul_f32_e32 v133, v5, v133
	v_mul_f32_e32 v134, v6, v134
	v_mul_f32_e32 v135, v7, v135
	v_mul_f32_e32 v128, v152, v128
	v_mul_f32_e32 v129, v153, v129
	v_mul_f32_e32 v130, v154, v130
	v_mul_f32_e32 v131, v155, v131
	v_mul_f32_e32 v132, v156, v132
	v_mul_f32_e32 v133, v157, v133
	v_mul_f32_e32 v134, v158, v134
	v_mul_f32_e32 v135, v159, v135
	v_cvt_pk_bf16_f32 v90, v128, v129
	v_cvt_pk_bf16_f32 v91, v130, v131
	v_cvt_pk_bf16_f32 v92, v132, v133
	v_cvt_pk_bf16_f32 v93, v134, v135
	global_store_dwordx2 v21, v[90:91], s[10:11]
	global_store_dwordx2 v21, v[92:93], s[10:11] offset:512
.Lpd_skip_L1_7:
	s_mul_i32 s16, s15, 8
	s_add_i32 s14, s14, s16
	s_cmp_lt_u32 s14, 0x4000
	s_cbranch_scc1 .Lpd_loop_L1
